# prep adaLN/PE gemv loops: 16-row blocks of the f32 weight streamed three blocks deep instead of 8 loads then a full wait; activations broadcast by DPP, same k order
# speedup vs baseline: 1.0060x; 1.0060x over previous
.LBB0_11:
	s_or_b64 exec, exec, s[20:21]
	s_mov_b64 s[20:21], s[0:1]
	s_waitcnt lgkmcnt(0)
	s_barrier
	s_load_dwordx2 s[22:23], s[20:21], 0x68
	s_mov_b64 s[20:21], s[0:1]
	s_lshl_b32 s12, s27, 2
	s_load_dwordx2 s[20:21], s[20:21], 0x70
	s_and_b32 s12, s12, 0x300
	v_lshlrev_b64 v[16:17], 21, v[14:15]
	s_waitcnt lgkmcnt(0)
	v_lshl_add_u64 v[18:19], s[22:23], 0, v[4:5]
	v_or_b32_e32 v16, s12, v16
	v_lshl_add_u64 v[16:17], v[18:19], 0, v[16:17]
	v_mov_b32_e32 v18, 0
	s_mov_b64 s[22:23], 0
	v_mov_b32_e32 v25, v7
	v_mov_b32_e32 v19, v18
	s_mov_b32 s42, 0x400
	s_mov_b32 s43, 0
	v_mov_b64_e32 v[136:137], v[16:17]
	v_mbcnt_lo_u32_b32 v139, -1, 0
	v_mbcnt_hi_u32_b32 v139, -1, v139
	v_and_b32_e32 v139, 15, v139
	v_lshl_add_u32 v138, v139, 2, v25
	ds_read_b32 v128, v138
	ds_read_b32 v132, v138 offset:8192
	v_add_u32_e32 v138, 64, v138
	global_load_dword v64, v[136:137], off
	v_lshl_add_u64 v[136:137], v[136:137], 0, s[42:43]
	global_load_dword v65, v[136:137], off
	v_lshl_add_u64 v[136:137], v[136:137], 0, s[42:43]
	global_load_dword v66, v[136:137], off
	v_lshl_add_u64 v[136:137], v[136:137], 0, s[42:43]
	global_load_dword v67, v[136:137], off
	v_lshl_add_u64 v[136:137], v[136:137], 0, s[42:43]
	global_load_dword v68, v[136:137], off
	v_lshl_add_u64 v[136:137], v[136:137], 0, s[42:43]
	global_load_dword v69, v[136:137], off
	v_lshl_add_u64 v[136:137], v[136:137], 0, s[42:43]
	global_load_dword v70, v[136:137], off
	v_lshl_add_u64 v[136:137], v[136:137], 0, s[42:43]
	global_load_dword v71, v[136:137], off
	v_lshl_add_u64 v[136:137], v[136:137], 0, s[42:43]
	global_load_dword v72, v[136:137], off
	v_lshl_add_u64 v[136:137], v[136:137], 0, s[42:43]
	global_load_dword v73, v[136:137], off
	v_lshl_add_u64 v[136:137], v[136:137], 0, s[42:43]
	global_load_dword v74, v[136:137], off
	v_lshl_add_u64 v[136:137], v[136:137], 0, s[42:43]
	global_load_dword v75, v[136:137], off
	v_lshl_add_u64 v[136:137], v[136:137], 0, s[42:43]
	global_load_dword v76, v[136:137], off
	v_lshl_add_u64 v[136:137], v[136:137], 0, s[42:43]
	global_load_dword v77, v[136:137], off
	v_lshl_add_u64 v[136:137], v[136:137], 0, s[42:43]
	global_load_dword v78, v[136:137], off
	v_lshl_add_u64 v[136:137], v[136:137], 0, s[42:43]
	global_load_dword v79, v[136:137], off
	v_lshl_add_u64 v[136:137], v[136:137], 0, s[42:43]
	ds_read_b32 v129, v138
	ds_read_b32 v133, v138 offset:8192
	v_add_u32_e32 v138, 64, v138
	global_load_dword v80, v[136:137], off
	v_lshl_add_u64 v[136:137], v[136:137], 0, s[42:43]
	global_load_dword v81, v[136:137], off
	v_lshl_add_u64 v[136:137], v[136:137], 0, s[42:43]
	global_load_dword v82, v[136:137], off
	v_lshl_add_u64 v[136:137], v[136:137], 0, s[42:43]
	global_load_dword v83, v[136:137], off
	v_lshl_add_u64 v[136:137], v[136:137], 0, s[42:43]
	global_load_dword v84, v[136:137], off
	v_lshl_add_u64 v[136:137], v[136:137], 0, s[42:43]
	global_load_dword v85, v[136:137], off
	v_lshl_add_u64 v[136:137], v[136:137], 0, s[42:43]
	global_load_dword v86, v[136:137], off
	v_lshl_add_u64 v[136:137], v[136:137], 0, s[42:43]
	global_load_dword v87, v[136:137], off
	v_lshl_add_u64 v[136:137], v[136:137], 0, s[42:43]
	global_load_dword v88, v[136:137], off
	v_lshl_add_u64 v[136:137], v[136:137], 0, s[42:43]
	global_load_dword v89, v[136:137], off
	v_lshl_add_u64 v[136:137], v[136:137], 0, s[42:43]
	global_load_dword v90, v[136:137], off
	v_lshl_add_u64 v[136:137], v[136:137], 0, s[42:43]
	global_load_dword v91, v[136:137], off
	v_lshl_add_u64 v[136:137], v[136:137], 0, s[42:43]
	global_load_dword v92, v[136:137], off
	v_lshl_add_u64 v[136:137], v[136:137], 0, s[42:43]
	global_load_dword v93, v[136:137], off
	v_lshl_add_u64 v[136:137], v[136:137], 0, s[42:43]
	global_load_dword v94, v[136:137], off
	v_lshl_add_u64 v[136:137], v[136:137], 0, s[42:43]
	global_load_dword v95, v[136:137], off
	v_lshl_add_u64 v[136:137], v[136:137], 0, s[42:43]
	ds_read_b32 v130, v138
	ds_read_b32 v134, v138 offset:8192
	v_add_u32_e32 v138, 64, v138
	global_load_dword v96, v[136:137], off
	v_lshl_add_u64 v[136:137], v[136:137], 0, s[42:43]
	global_load_dword v97, v[136:137], off
	v_lshl_add_u64 v[136:137], v[136:137], 0, s[42:43]
	global_load_dword v98, v[136:137], off
	v_lshl_add_u64 v[136:137], v[136:137], 0, s[42:43]
	global_load_dword v99, v[136:137], off
	v_lshl_add_u64 v[136:137], v[136:137], 0, s[42:43]
	global_load_dword v100, v[136:137], off
	v_lshl_add_u64 v[136:137], v[136:137], 0, s[42:43]
	global_load_dword v101, v[136:137], off
	v_lshl_add_u64 v[136:137], v[136:137], 0, s[42:43]
	global_load_dword v102, v[136:137], off
	v_lshl_add_u64 v[136:137], v[136:137], 0, s[42:43]
	global_load_dword v103, v[136:137], off
	v_lshl_add_u64 v[136:137], v[136:137], 0, s[42:43]
	global_load_dword v104, v[136:137], off
	v_lshl_add_u64 v[136:137], v[136:137], 0, s[42:43]
	global_load_dword v105, v[136:137], off
	v_lshl_add_u64 v[136:137], v[136:137], 0, s[42:43]
	global_load_dword v106, v[136:137], off
	v_lshl_add_u64 v[136:137], v[136:137], 0, s[42:43]
	global_load_dword v107, v[136:137], off
	v_lshl_add_u64 v[136:137], v[136:137], 0, s[42:43]
	global_load_dword v108, v[136:137], off
	v_lshl_add_u64 v[136:137], v[136:137], 0, s[42:43]
	global_load_dword v109, v[136:137], off
	v_lshl_add_u64 v[136:137], v[136:137], 0, s[42:43]
	global_load_dword v110, v[136:137], off
	v_lshl_add_u64 v[136:137], v[136:137], 0, s[42:43]
	global_load_dword v111, v[136:137], off
	v_lshl_add_u64 v[136:137], v[136:137], 0, s[42:43]
	s_mov_b32 s44, 0
pgv_a_loop:
	s_waitcnt vmcnt(32) lgkmcnt(0)
	ds_read_b32 v131, v138
	ds_read_b32 v135, v138 offset:8192
	v_add_u32_e32 v138, 64, v138
	global_load_dword v112, v[136:137], off
	v_lshl_add_u64 v[136:137], v[136:137], 0, s[42:43]
	global_load_dword v113, v[136:137], off
	v_lshl_add_u64 v[136:137], v[136:137], 0, s[42:43]
	global_load_dword v114, v[136:137], off
	v_lshl_add_u64 v[136:137], v[136:137], 0, s[42:43]
	global_load_dword v115, v[136:137], off
	v_lshl_add_u64 v[136:137], v[136:137], 0, s[42:43]
	global_load_dword v116, v[136:137], off
	v_lshl_add_u64 v[136:137], v[136:137], 0, s[42:43]
	global_load_dword v117, v[136:137], off
	v_lshl_add_u64 v[136:137], v[136:137], 0, s[42:43]
	global_load_dword v118, v[136:137], off
	v_lshl_add_u64 v[136:137], v[136:137], 0, s[42:43]
	global_load_dword v119, v[136:137], off
	v_lshl_add_u64 v[136:137], v[136:137], 0, s[42:43]
	global_load_dword v120, v[136:137], off
	v_lshl_add_u64 v[136:137], v[136:137], 0, s[42:43]
	global_load_dword v121, v[136:137], off
	v_lshl_add_u64 v[136:137], v[136:137], 0, s[42:43]
	global_load_dword v122, v[136:137], off
	v_lshl_add_u64 v[136:137], v[136:137], 0, s[42:43]
	global_load_dword v123, v[136:137], off
	v_lshl_add_u64 v[136:137], v[136:137], 0, s[42:43]
	global_load_dword v124, v[136:137], off
	v_lshl_add_u64 v[136:137], v[136:137], 0, s[42:43]
	global_load_dword v125, v[136:137], off
	v_lshl_add_u64 v[136:137], v[136:137], 0, s[42:43]
	global_load_dword v126, v[136:137], off
	v_lshl_add_u64 v[136:137], v[136:137], 0, s[42:43]
	global_load_dword v127, v[136:137], off
	v_lshl_add_u64 v[136:137], v[136:137], 0, s[42:43]
	v_fmac_f32_dpp v18, v128, v64 row_newbcast:0 row_mask:0xf bank_mask:0xf
	v_fmac_f32_dpp v19, v132, v64 row_newbcast:0 row_mask:0xf bank_mask:0xf
	v_fmac_f32_dpp v18, v128, v65 row_newbcast:1 row_mask:0xf bank_mask:0xf
	v_fmac_f32_dpp v19, v132, v65 row_newbcast:1 row_mask:0xf bank_mask:0xf
	v_fmac_f32_dpp v18, v128, v66 row_newbcast:2 row_mask:0xf bank_mask:0xf
	v_fmac_f32_dpp v19, v132, v66 row_newbcast:2 row_mask:0xf bank_mask:0xf
	v_fmac_f32_dpp v18, v128, v67 row_newbcast:3 row_mask:0xf bank_mask:0xf
	v_fmac_f32_dpp v19, v132, v67 row_newbcast:3 row_mask:0xf bank_mask:0xf
	v_fmac_f32_dpp v18, v128, v68 row_newbcast:4 row_mask:0xf bank_mask:0xf
	v_fmac_f32_dpp v19, v132, v68 row_newbcast:4 row_mask:0xf bank_mask:0xf
	v_fmac_f32_dpp v18, v128, v69 row_newbcast:5 row_mask:0xf bank_mask:0xf
	v_fmac_f32_dpp v19, v132, v69 row_newbcast:5 row_mask:0xf bank_mask:0xf
	v_fmac_f32_dpp v18, v128, v70 row_newbcast:6 row_mask:0xf bank_mask:0xf
	v_fmac_f32_dpp v19, v132, v70 row_newbcast:6 row_mask:0xf bank_mask:0xf
	v_fmac_f32_dpp v18, v128, v71 row_newbcast:7 row_mask:0xf bank_mask:0xf
	v_fmac_f32_dpp v19, v132, v71 row_newbcast:7 row_mask:0xf bank_mask:0xf
	v_fmac_f32_dpp v18, v128, v72 row_newbcast:8 row_mask:0xf bank_mask:0xf
	v_fmac_f32_dpp v19, v132, v72 row_newbcast:8 row_mask:0xf bank_mask:0xf
	v_fmac_f32_dpp v18, v128, v73 row_newbcast:9 row_mask:0xf bank_mask:0xf
	v_fmac_f32_dpp v19, v132, v73 row_newbcast:9 row_mask:0xf bank_mask:0xf
	v_fmac_f32_dpp v18, v128, v74 row_newbcast:10 row_mask:0xf bank_mask:0xf
	v_fmac_f32_dpp v19, v132, v74 row_newbcast:10 row_mask:0xf bank_mask:0xf
	v_fmac_f32_dpp v18, v128, v75 row_newbcast:11 row_mask:0xf bank_mask:0xf
	v_fmac_f32_dpp v19, v132, v75 row_newbcast:11 row_mask:0xf bank_mask:0xf
	v_fmac_f32_dpp v18, v128, v76 row_newbcast:12 row_mask:0xf bank_mask:0xf
	v_fmac_f32_dpp v19, v132, v76 row_newbcast:12 row_mask:0xf bank_mask:0xf
	v_fmac_f32_dpp v18, v128, v77 row_newbcast:13 row_mask:0xf bank_mask:0xf
	v_fmac_f32_dpp v19, v132, v77 row_newbcast:13 row_mask:0xf bank_mask:0xf
	v_fmac_f32_dpp v18, v128, v78 row_newbcast:14 row_mask:0xf bank_mask:0xf
	v_fmac_f32_dpp v19, v132, v78 row_newbcast:14 row_mask:0xf bank_mask:0xf
	v_fmac_f32_dpp v18, v128, v79 row_newbcast:15 row_mask:0xf bank_mask:0xf
	v_fmac_f32_dpp v19, v132, v79 row_newbcast:15 row_mask:0xf bank_mask:0xf
	s_waitcnt vmcnt(32) lgkmcnt(0)
	ds_read_b32 v128, v138
	ds_read_b32 v132, v138 offset:8192
	v_add_u32_e32 v138, 64, v138
	global_load_dword v64, v[136:137], off
	v_lshl_add_u64 v[136:137], v[136:137], 0, s[42:43]
	global_load_dword v65, v[136:137], off
	v_lshl_add_u64 v[136:137], v[136:137], 0, s[42:43]
	global_load_dword v66, v[136:137], off
	v_lshl_add_u64 v[136:137], v[136:137], 0, s[42:43]
	global_load_dword v67, v[136:137], off
	v_lshl_add_u64 v[136:137], v[136:137], 0, s[42:43]
	global_load_dword v68, v[136:137], off
	v_lshl_add_u64 v[136:137], v[136:137], 0, s[42:43]
	global_load_dword v69, v[136:137], off
	v_lshl_add_u64 v[136:137], v[136:137], 0, s[42:43]
	global_load_dword v70, v[136:137], off
	v_lshl_add_u64 v[136:137], v[136:137], 0, s[42:43]
	global_load_dword v71, v[136:137], off
	v_lshl_add_u64 v[136:137], v[136:137], 0, s[42:43]
	global_load_dword v72, v[136:137], off
	v_lshl_add_u64 v[136:137], v[136:137], 0, s[42:43]
	global_load_dword v73, v[136:137], off
	v_lshl_add_u64 v[136:137], v[136:137], 0, s[42:43]
	global_load_dword v74, v[136:137], off
	v_lshl_add_u64 v[136:137], v[136:137], 0, s[42:43]
	global_load_dword v75, v[136:137], off
	v_lshl_add_u64 v[136:137], v[136:137], 0, s[42:43]
	global_load_dword v76, v[136:137], off
	v_lshl_add_u64 v[136:137], v[136:137], 0, s[42:43]
	global_load_dword v77, v[136:137], off
	v_lshl_add_u64 v[136:137], v[136:137], 0, s[42:43]
	global_load_dword v78, v[136:137], off
	v_lshl_add_u64 v[136:137], v[136:137], 0, s[42:43]
	global_load_dword v79, v[136:137], off
	v_lshl_add_u64 v[136:137], v[136:137], 0, s[42:43]
	v_fmac_f32_dpp v18, v129, v80 row_newbcast:0 row_mask:0xf bank_mask:0xf
	v_fmac_f32_dpp v19, v133, v80 row_newbcast:0 row_mask:0xf bank_mask:0xf
	v_fmac_f32_dpp v18, v129, v81 row_newbcast:1 row_mask:0xf bank_mask:0xf
	v_fmac_f32_dpp v19, v133, v81 row_newbcast:1 row_mask:0xf bank_mask:0xf
	v_fmac_f32_dpp v18, v129, v82 row_newbcast:2 row_mask:0xf bank_mask:0xf
	v_fmac_f32_dpp v19, v133, v82 row_newbcast:2 row_mask:0xf bank_mask:0xf
	v_fmac_f32_dpp v18, v129, v83 row_newbcast:3 row_mask:0xf bank_mask:0xf
	v_fmac_f32_dpp v19, v133, v83 row_newbcast:3 row_mask:0xf bank_mask:0xf
	v_fmac_f32_dpp v18, v129, v84 row_newbcast:4 row_mask:0xf bank_mask:0xf
	v_fmac_f32_dpp v19, v133, v84 row_newbcast:4 row_mask:0xf bank_mask:0xf
	v_fmac_f32_dpp v18, v129, v85 row_newbcast:5 row_mask:0xf bank_mask:0xf
	v_fmac_f32_dpp v19, v133, v85 row_newbcast:5 row_mask:0xf bank_mask:0xf
	v_fmac_f32_dpp v18, v129, v86 row_newbcast:6 row_mask:0xf bank_mask:0xf
	v_fmac_f32_dpp v19, v133, v86 row_newbcast:6 row_mask:0xf bank_mask:0xf
	v_fmac_f32_dpp v18, v129, v87 row_newbcast:7 row_mask:0xf bank_mask:0xf
	v_fmac_f32_dpp v19, v133, v87 row_newbcast:7 row_mask:0xf bank_mask:0xf
	v_fmac_f32_dpp v18, v129, v88 row_newbcast:8 row_mask:0xf bank_mask:0xf
	v_fmac_f32_dpp v19, v133, v88 row_newbcast:8 row_mask:0xf bank_mask:0xf
	v_fmac_f32_dpp v18, v129, v89 row_newbcast:9 row_mask:0xf bank_mask:0xf
	v_fmac_f32_dpp v19, v133, v89 row_newbcast:9 row_mask:0xf bank_mask:0xf
	v_fmac_f32_dpp v18, v129, v90 row_newbcast:10 row_mask:0xf bank_mask:0xf
	v_fmac_f32_dpp v19, v133, v90 row_newbcast:10 row_mask:0xf bank_mask:0xf
	v_fmac_f32_dpp v18, v129, v91 row_newbcast:11 row_mask:0xf bank_mask:0xf
	v_fmac_f32_dpp v19, v133, v91 row_newbcast:11 row_mask:0xf bank_mask:0xf
	v_fmac_f32_dpp v18, v129, v92 row_newbcast:12 row_mask:0xf bank_mask:0xf
	v_fmac_f32_dpp v19, v133, v92 row_newbcast:12 row_mask:0xf bank_mask:0xf
	v_fmac_f32_dpp v18, v129, v93 row_newbcast:13 row_mask:0xf bank_mask:0xf
	v_fmac_f32_dpp v19, v133, v93 row_newbcast:13 row_mask:0xf bank_mask:0xf
	v_fmac_f32_dpp v18, v129, v94 row_newbcast:14 row_mask:0xf bank_mask:0xf
	v_fmac_f32_dpp v19, v133, v94 row_newbcast:14 row_mask:0xf bank_mask:0xf
	v_fmac_f32_dpp v18, v129, v95 row_newbcast:15 row_mask:0xf bank_mask:0xf
	v_fmac_f32_dpp v19, v133, v95 row_newbcast:15 row_mask:0xf bank_mask:0xf
	s_waitcnt vmcnt(32) lgkmcnt(0)
	ds_read_b32 v129, v138
	ds_read_b32 v133, v138 offset:8192
	v_add_u32_e32 v138, 64, v138
	global_load_dword v80, v[136:137], off
	v_lshl_add_u64 v[136:137], v[136:137], 0, s[42:43]
	global_load_dword v81, v[136:137], off
	v_lshl_add_u64 v[136:137], v[136:137], 0, s[42:43]
	global_load_dword v82, v[136:137], off
	v_lshl_add_u64 v[136:137], v[136:137], 0, s[42:43]
	global_load_dword v83, v[136:137], off
	v_lshl_add_u64 v[136:137], v[136:137], 0, s[42:43]
	global_load_dword v84, v[136:137], off
	v_lshl_add_u64 v[136:137], v[136:137], 0, s[42:43]
	global_load_dword v85, v[136:137], off
	v_lshl_add_u64 v[136:137], v[136:137], 0, s[42:43]
	global_load_dword v86, v[136:137], off
	v_lshl_add_u64 v[136:137], v[136:137], 0, s[42:43]
	global_load_dword v87, v[136:137], off
	v_lshl_add_u64 v[136:137], v[136:137], 0, s[42:43]
	global_load_dword v88, v[136:137], off
	v_lshl_add_u64 v[136:137], v[136:137], 0, s[42:43]
	global_load_dword v89, v[136:137], off
	v_lshl_add_u64 v[136:137], v[136:137], 0, s[42:43]
	global_load_dword v90, v[136:137], off
	v_lshl_add_u64 v[136:137], v[136:137], 0, s[42:43]
	global_load_dword v91, v[136:137], off
	v_lshl_add_u64 v[136:137], v[136:137], 0, s[42:43]
	global_load_dword v92, v[136:137], off
	v_lshl_add_u64 v[136:137], v[136:137], 0, s[42:43]
	global_load_dword v93, v[136:137], off
	v_lshl_add_u64 v[136:137], v[136:137], 0, s[42:43]
	global_load_dword v94, v[136:137], off
	v_lshl_add_u64 v[136:137], v[136:137], 0, s[42:43]
	global_load_dword v95, v[136:137], off
	v_lshl_add_u64 v[136:137], v[136:137], 0, s[42:43]
	v_fmac_f32_dpp v18, v130, v96 row_newbcast:0 row_mask:0xf bank_mask:0xf
	v_fmac_f32_dpp v19, v134, v96 row_newbcast:0 row_mask:0xf bank_mask:0xf
	v_fmac_f32_dpp v18, v130, v97 row_newbcast:1 row_mask:0xf bank_mask:0xf
	v_fmac_f32_dpp v19, v134, v97 row_newbcast:1 row_mask:0xf bank_mask:0xf
	v_fmac_f32_dpp v18, v130, v98 row_newbcast:2 row_mask:0xf bank_mask:0xf
	v_fmac_f32_dpp v19, v134, v98 row_newbcast:2 row_mask:0xf bank_mask:0xf
	v_fmac_f32_dpp v18, v130, v99 row_newbcast:3 row_mask:0xf bank_mask:0xf
	v_fmac_f32_dpp v19, v134, v99 row_newbcast:3 row_mask:0xf bank_mask:0xf
	v_fmac_f32_dpp v18, v130, v100 row_newbcast:4 row_mask:0xf bank_mask:0xf
	v_fmac_f32_dpp v19, v134, v100 row_newbcast:4 row_mask:0xf bank_mask:0xf
	v_fmac_f32_dpp v18, v130, v101 row_newbcast:5 row_mask:0xf bank_mask:0xf
	v_fmac_f32_dpp v19, v134, v101 row_newbcast:5 row_mask:0xf bank_mask:0xf
	v_fmac_f32_dpp v18, v130, v102 row_newbcast:6 row_mask:0xf bank_mask:0xf
	v_fmac_f32_dpp v19, v134, v102 row_newbcast:6 row_mask:0xf bank_mask:0xf
	v_fmac_f32_dpp v18, v130, v103 row_newbcast:7 row_mask:0xf bank_mask:0xf
	v_fmac_f32_dpp v19, v134, v103 row_newbcast:7 row_mask:0xf bank_mask:0xf
	v_fmac_f32_dpp v18, v130, v104 row_newbcast:8 row_mask:0xf bank_mask:0xf
	v_fmac_f32_dpp v19, v134, v104 row_newbcast:8 row_mask:0xf bank_mask:0xf
	v_fmac_f32_dpp v18, v130, v105 row_newbcast:9 row_mask:0xf bank_mask:0xf
	v_fmac_f32_dpp v19, v134, v105 row_newbcast:9 row_mask:0xf bank_mask:0xf
	v_fmac_f32_dpp v18, v130, v106 row_newbcast:10 row_mask:0xf bank_mask:0xf
	v_fmac_f32_dpp v19, v134, v106 row_newbcast:10 row_mask:0xf bank_mask:0xf
	v_fmac_f32_dpp v18, v130, v107 row_newbcast:11 row_mask:0xf bank_mask:0xf
	v_fmac_f32_dpp v19, v134, v107 row_newbcast:11 row_mask:0xf bank_mask:0xf
	v_fmac_f32_dpp v18, v130, v108 row_newbcast:12 row_mask:0xf bank_mask:0xf
	v_fmac_f32_dpp v19, v134, v108 row_newbcast:12 row_mask:0xf bank_mask:0xf
	v_fmac_f32_dpp v18, v130, v109 row_newbcast:13 row_mask:0xf bank_mask:0xf
	v_fmac_f32_dpp v19, v134, v109 row_newbcast:13 row_mask:0xf bank_mask:0xf
	v_fmac_f32_dpp v18, v130, v110 row_newbcast:14 row_mask:0xf bank_mask:0xf
	v_fmac_f32_dpp v19, v134, v110 row_newbcast:14 row_mask:0xf bank_mask:0xf
	v_fmac_f32_dpp v18, v130, v111 row_newbcast:15 row_mask:0xf bank_mask:0xf
	v_fmac_f32_dpp v19, v134, v111 row_newbcast:15 row_mask:0xf bank_mask:0xf
	s_waitcnt vmcnt(32) lgkmcnt(0)
	ds_read_b32 v130, v138
	ds_read_b32 v134, v138 offset:8192
	v_add_u32_e32 v138, 64, v138
	global_load_dword v96, v[136:137], off
	v_lshl_add_u64 v[136:137], v[136:137], 0, s[42:43]
	global_load_dword v97, v[136:137], off
	v_lshl_add_u64 v[136:137], v[136:137], 0, s[42:43]
	global_load_dword v98, v[136:137], off
	v_lshl_add_u64 v[136:137], v[136:137], 0, s[42:43]
	global_load_dword v99, v[136:137], off
	v_lshl_add_u64 v[136:137], v[136:137], 0, s[42:43]
	global_load_dword v100, v[136:137], off
	v_lshl_add_u64 v[136:137], v[136:137], 0, s[42:43]
	global_load_dword v101, v[136:137], off
	v_lshl_add_u64 v[136:137], v[136:137], 0, s[42:43]
	global_load_dword v102, v[136:137], off
	v_lshl_add_u64 v[136:137], v[136:137], 0, s[42:43]
	global_load_dword v103, v[136:137], off
	v_lshl_add_u64 v[136:137], v[136:137], 0, s[42:43]
	global_load_dword v104, v[136:137], off
	v_lshl_add_u64 v[136:137], v[136:137], 0, s[42:43]
	global_load_dword v105, v[136:137], off
	v_lshl_add_u64 v[136:137], v[136:137], 0, s[42:43]
	global_load_dword v106, v[136:137], off
	v_lshl_add_u64 v[136:137], v[136:137], 0, s[42:43]
	global_load_dword v107, v[136:137], off
	v_lshl_add_u64 v[136:137], v[136:137], 0, s[42:43]
	global_load_dword v108, v[136:137], off
	v_lshl_add_u64 v[136:137], v[136:137], 0, s[42:43]
	global_load_dword v109, v[136:137], off
	v_lshl_add_u64 v[136:137], v[136:137], 0, s[42:43]
	global_load_dword v110, v[136:137], off
	v_lshl_add_u64 v[136:137], v[136:137], 0, s[42:43]
	global_load_dword v111, v[136:137], off
	v_lshl_add_u64 v[136:137], v[136:137], 0, s[42:43]
	v_fmac_f32_dpp v18, v131, v112 row_newbcast:0 row_mask:0xf bank_mask:0xf
	v_fmac_f32_dpp v19, v135, v112 row_newbcast:0 row_mask:0xf bank_mask:0xf
	v_fmac_f32_dpp v18, v131, v113 row_newbcast:1 row_mask:0xf bank_mask:0xf
	v_fmac_f32_dpp v19, v135, v113 row_newbcast:1 row_mask:0xf bank_mask:0xf
	v_fmac_f32_dpp v18, v131, v114 row_newbcast:2 row_mask:0xf bank_mask:0xf
	v_fmac_f32_dpp v19, v135, v114 row_newbcast:2 row_mask:0xf bank_mask:0xf
	v_fmac_f32_dpp v18, v131, v115 row_newbcast:3 row_mask:0xf bank_mask:0xf
	v_fmac_f32_dpp v19, v135, v115 row_newbcast:3 row_mask:0xf bank_mask:0xf
	v_fmac_f32_dpp v18, v131, v116 row_newbcast:4 row_mask:0xf bank_mask:0xf
	v_fmac_f32_dpp v19, v135, v116 row_newbcast:4 row_mask:0xf bank_mask:0xf
	v_fmac_f32_dpp v18, v131, v117 row_newbcast:5 row_mask:0xf bank_mask:0xf
	v_fmac_f32_dpp v19, v135, v117 row_newbcast:5 row_mask:0xf bank_mask:0xf
	v_fmac_f32_dpp v18, v131, v118 row_newbcast:6 row_mask:0xf bank_mask:0xf
	v_fmac_f32_dpp v19, v135, v118 row_newbcast:6 row_mask:0xf bank_mask:0xf
	v_fmac_f32_dpp v18, v131, v119 row_newbcast:7 row_mask:0xf bank_mask:0xf
	v_fmac_f32_dpp v19, v135, v119 row_newbcast:7 row_mask:0xf bank_mask:0xf
	v_fmac_f32_dpp v18, v131, v120 row_newbcast:8 row_mask:0xf bank_mask:0xf
	v_fmac_f32_dpp v19, v135, v120 row_newbcast:8 row_mask:0xf bank_mask:0xf
	v_fmac_f32_dpp v18, v131, v121 row_newbcast:9 row_mask:0xf bank_mask:0xf
	v_fmac_f32_dpp v19, v135, v121 row_newbcast:9 row_mask:0xf bank_mask:0xf
	v_fmac_f32_dpp v18, v131, v122 row_newbcast:10 row_mask:0xf bank_mask:0xf
	v_fmac_f32_dpp v19, v135, v122 row_newbcast:10 row_mask:0xf bank_mask:0xf
	v_fmac_f32_dpp v18, v131, v123 row_newbcast:11 row_mask:0xf bank_mask:0xf
	v_fmac_f32_dpp v19, v135, v123 row_newbcast:11 row_mask:0xf bank_mask:0xf
	v_fmac_f32_dpp v18, v131, v124 row_newbcast:12 row_mask:0xf bank_mask:0xf
	v_fmac_f32_dpp v19, v135, v124 row_newbcast:12 row_mask:0xf bank_mask:0xf
	v_fmac_f32_dpp v18, v131, v125 row_newbcast:13 row_mask:0xf bank_mask:0xf
	v_fmac_f32_dpp v19, v135, v125 row_newbcast:13 row_mask:0xf bank_mask:0xf
	v_fmac_f32_dpp v18, v131, v126 row_newbcast:14 row_mask:0xf bank_mask:0xf
	v_fmac_f32_dpp v19, v135, v126 row_newbcast:14 row_mask:0xf bank_mask:0xf
	v_fmac_f32_dpp v18, v131, v127 row_newbcast:15 row_mask:0xf bank_mask:0xf
	v_fmac_f32_dpp v19, v135, v127 row_newbcast:15 row_mask:0xf bank_mask:0xf
	s_add_i32 s44, s44, 1
	s_cmp_lt_u32 s44, 3
	s_cbranch_scc1 pgv_a_loop
	s_waitcnt vmcnt(32) lgkmcnt(0)
	ds_read_b32 v131, v138
	ds_read_b32 v135, v138 offset:8192
	v_add_u32_e32 v138, 64, v138
	global_load_dword v112, v[136:137], off
	v_lshl_add_u64 v[136:137], v[136:137], 0, s[42:43]
	global_load_dword v113, v[136:137], off
	v_lshl_add_u64 v[136:137], v[136:137], 0, s[42:43]
	global_load_dword v114, v[136:137], off
	v_lshl_add_u64 v[136:137], v[136:137], 0, s[42:43]
	global_load_dword v115, v[136:137], off
	v_lshl_add_u64 v[136:137], v[136:137], 0, s[42:43]
	global_load_dword v116, v[136:137], off
	v_lshl_add_u64 v[136:137], v[136:137], 0, s[42:43]
	global_load_dword v117, v[136:137], off
	v_lshl_add_u64 v[136:137], v[136:137], 0, s[42:43]
	global_load_dword v118, v[136:137], off
	v_lshl_add_u64 v[136:137], v[136:137], 0, s[42:43]
	global_load_dword v119, v[136:137], off
	v_lshl_add_u64 v[136:137], v[136:137], 0, s[42:43]
	global_load_dword v120, v[136:137], off
	v_lshl_add_u64 v[136:137], v[136:137], 0, s[42:43]
	global_load_dword v121, v[136:137], off
	v_lshl_add_u64 v[136:137], v[136:137], 0, s[42:43]
	global_load_dword v122, v[136:137], off
	v_lshl_add_u64 v[136:137], v[136:137], 0, s[42:43]
	global_load_dword v123, v[136:137], off
	v_lshl_add_u64 v[136:137], v[136:137], 0, s[42:43]
	global_load_dword v124, v[136:137], off
	v_lshl_add_u64 v[136:137], v[136:137], 0, s[42:43]
	global_load_dword v125, v[136:137], off
	v_lshl_add_u64 v[136:137], v[136:137], 0, s[42:43]
	global_load_dword v126, v[136:137], off
	v_lshl_add_u64 v[136:137], v[136:137], 0, s[42:43]
	global_load_dword v127, v[136:137], off
	v_lshl_add_u64 v[136:137], v[136:137], 0, s[42:43]
	v_fmac_f32_dpp v18, v128, v64 row_newbcast:0 row_mask:0xf bank_mask:0xf
	v_fmac_f32_dpp v19, v132, v64 row_newbcast:0 row_mask:0xf bank_mask:0xf
	v_fmac_f32_dpp v18, v128, v65 row_newbcast:1 row_mask:0xf bank_mask:0xf
	v_fmac_f32_dpp v19, v132, v65 row_newbcast:1 row_mask:0xf bank_mask:0xf
	v_fmac_f32_dpp v18, v128, v66 row_newbcast:2 row_mask:0xf bank_mask:0xf
	v_fmac_f32_dpp v19, v132, v66 row_newbcast:2 row_mask:0xf bank_mask:0xf
	v_fmac_f32_dpp v18, v128, v67 row_newbcast:3 row_mask:0xf bank_mask:0xf
	v_fmac_f32_dpp v19, v132, v67 row_newbcast:3 row_mask:0xf bank_mask:0xf
	v_fmac_f32_dpp v18, v128, v68 row_newbcast:4 row_mask:0xf bank_mask:0xf
	v_fmac_f32_dpp v19, v132, v68 row_newbcast:4 row_mask:0xf bank_mask:0xf
	v_fmac_f32_dpp v18, v128, v69 row_newbcast:5 row_mask:0xf bank_mask:0xf
	v_fmac_f32_dpp v19, v132, v69 row_newbcast:5 row_mask:0xf bank_mask:0xf
	v_fmac_f32_dpp v18, v128, v70 row_newbcast:6 row_mask:0xf bank_mask:0xf
	v_fmac_f32_dpp v19, v132, v70 row_newbcast:6 row_mask:0xf bank_mask:0xf
	v_fmac_f32_dpp v18, v128, v71 row_newbcast:7 row_mask:0xf bank_mask:0xf
	v_fmac_f32_dpp v19, v132, v71 row_newbcast:7 row_mask:0xf bank_mask:0xf
	v_fmac_f32_dpp v18, v128, v72 row_newbcast:8 row_mask:0xf bank_mask:0xf
	v_fmac_f32_dpp v19, v132, v72 row_newbcast:8 row_mask:0xf bank_mask:0xf
	v_fmac_f32_dpp v18, v128, v73 row_newbcast:9 row_mask:0xf bank_mask:0xf
	v_fmac_f32_dpp v19, v132, v73 row_newbcast:9 row_mask:0xf bank_mask:0xf
	v_fmac_f32_dpp v18, v128, v74 row_newbcast:10 row_mask:0xf bank_mask:0xf
	v_fmac_f32_dpp v19, v132, v74 row_newbcast:10 row_mask:0xf bank_mask:0xf
	v_fmac_f32_dpp v18, v128, v75 row_newbcast:11 row_mask:0xf bank_mask:0xf
	v_fmac_f32_dpp v19, v132, v75 row_newbcast:11 row_mask:0xf bank_mask:0xf
	v_fmac_f32_dpp v18, v128, v76 row_newbcast:12 row_mask:0xf bank_mask:0xf
	v_fmac_f32_dpp v19, v132, v76 row_newbcast:12 row_mask:0xf bank_mask:0xf
	v_fmac_f32_dpp v18, v128, v77 row_newbcast:13 row_mask:0xf bank_mask:0xf
	v_fmac_f32_dpp v19, v132, v77 row_newbcast:13 row_mask:0xf bank_mask:0xf
	v_fmac_f32_dpp v18, v128, v78 row_newbcast:14 row_mask:0xf bank_mask:0xf
	v_fmac_f32_dpp v19, v132, v78 row_newbcast:14 row_mask:0xf bank_mask:0xf
	v_fmac_f32_dpp v18, v128, v79 row_newbcast:15 row_mask:0xf bank_mask:0xf
	v_fmac_f32_dpp v19, v132, v79 row_newbcast:15 row_mask:0xf bank_mask:0xf
	s_waitcnt vmcnt(32) lgkmcnt(0)
	v_fmac_f32_dpp v18, v129, v80 row_newbcast:0 row_mask:0xf bank_mask:0xf
	v_fmac_f32_dpp v19, v133, v80 row_newbcast:0 row_mask:0xf bank_mask:0xf
	v_fmac_f32_dpp v18, v129, v81 row_newbcast:1 row_mask:0xf bank_mask:0xf
	v_fmac_f32_dpp v19, v133, v81 row_newbcast:1 row_mask:0xf bank_mask:0xf
	v_fmac_f32_dpp v18, v129, v82 row_newbcast:2 row_mask:0xf bank_mask:0xf
	v_fmac_f32_dpp v19, v133, v82 row_newbcast:2 row_mask:0xf bank_mask:0xf
	v_fmac_f32_dpp v18, v129, v83 row_newbcast:3 row_mask:0xf bank_mask:0xf
	v_fmac_f32_dpp v19, v133, v83 row_newbcast:3 row_mask:0xf bank_mask:0xf
	v_fmac_f32_dpp v18, v129, v84 row_newbcast:4 row_mask:0xf bank_mask:0xf
	v_fmac_f32_dpp v19, v133, v84 row_newbcast:4 row_mask:0xf bank_mask:0xf
	v_fmac_f32_dpp v18, v129, v85 row_newbcast:5 row_mask:0xf bank_mask:0xf
	v_fmac_f32_dpp v19, v133, v85 row_newbcast:5 row_mask:0xf bank_mask:0xf
	v_fmac_f32_dpp v18, v129, v86 row_newbcast:6 row_mask:0xf bank_mask:0xf
	v_fmac_f32_dpp v19, v133, v86 row_newbcast:6 row_mask:0xf bank_mask:0xf
	v_fmac_f32_dpp v18, v129, v87 row_newbcast:7 row_mask:0xf bank_mask:0xf
	v_fmac_f32_dpp v19, v133, v87 row_newbcast:7 row_mask:0xf bank_mask:0xf
	v_fmac_f32_dpp v18, v129, v88 row_newbcast:8 row_mask:0xf bank_mask:0xf
	v_fmac_f32_dpp v19, v133, v88 row_newbcast:8 row_mask:0xf bank_mask:0xf
	v_fmac_f32_dpp v18, v129, v89 row_newbcast:9 row_mask:0xf bank_mask:0xf
	v_fmac_f32_dpp v19, v133, v89 row_newbcast:9 row_mask:0xf bank_mask:0xf
	v_fmac_f32_dpp v18, v129, v90 row_newbcast:10 row_mask:0xf bank_mask:0xf
	v_fmac_f32_dpp v19, v133, v90 row_newbcast:10 row_mask:0xf bank_mask:0xf
	v_fmac_f32_dpp v18, v129, v91 row_newbcast:11 row_mask:0xf bank_mask:0xf
	v_fmac_f32_dpp v19, v133, v91 row_newbcast:11 row_mask:0xf bank_mask:0xf
	v_fmac_f32_dpp v18, v129, v92 row_newbcast:12 row_mask:0xf bank_mask:0xf
	v_fmac_f32_dpp v19, v133, v92 row_newbcast:12 row_mask:0xf bank_mask:0xf
	v_fmac_f32_dpp v18, v129, v93 row_newbcast:13 row_mask:0xf bank_mask:0xf
	v_fmac_f32_dpp v19, v133, v93 row_newbcast:13 row_mask:0xf bank_mask:0xf
	v_fmac_f32_dpp v18, v129, v94 row_newbcast:14 row_mask:0xf bank_mask:0xf
	v_fmac_f32_dpp v19, v133, v94 row_newbcast:14 row_mask:0xf bank_mask:0xf
	v_fmac_f32_dpp v18, v129, v95 row_newbcast:15 row_mask:0xf bank_mask:0xf
	v_fmac_f32_dpp v19, v133, v95 row_newbcast:15 row_mask:0xf bank_mask:0xf
	s_waitcnt vmcnt(16)
	v_fmac_f32_dpp v18, v130, v96 row_newbcast:0 row_mask:0xf bank_mask:0xf
	v_fmac_f32_dpp v19, v134, v96 row_newbcast:0 row_mask:0xf bank_mask:0xf
	v_fmac_f32_dpp v18, v130, v97 row_newbcast:1 row_mask:0xf bank_mask:0xf
	v_fmac_f32_dpp v19, v134, v97 row_newbcast:1 row_mask:0xf bank_mask:0xf
	v_fmac_f32_dpp v18, v130, v98 row_newbcast:2 row_mask:0xf bank_mask:0xf
	v_fmac_f32_dpp v19, v134, v98 row_newbcast:2 row_mask:0xf bank_mask:0xf
	v_fmac_f32_dpp v18, v130, v99 row_newbcast:3 row_mask:0xf bank_mask:0xf
	v_fmac_f32_dpp v19, v134, v99 row_newbcast:3 row_mask:0xf bank_mask:0xf
	v_fmac_f32_dpp v18, v130, v100 row_newbcast:4 row_mask:0xf bank_mask:0xf
	v_fmac_f32_dpp v19, v134, v100 row_newbcast:4 row_mask:0xf bank_mask:0xf
	v_fmac_f32_dpp v18, v130, v101 row_newbcast:5 row_mask:0xf bank_mask:0xf
	v_fmac_f32_dpp v19, v134, v101 row_newbcast:5 row_mask:0xf bank_mask:0xf
	v_fmac_f32_dpp v18, v130, v102 row_newbcast:6 row_mask:0xf bank_mask:0xf
	v_fmac_f32_dpp v19, v134, v102 row_newbcast:6 row_mask:0xf bank_mask:0xf
	v_fmac_f32_dpp v18, v130, v103 row_newbcast:7 row_mask:0xf bank_mask:0xf
	v_fmac_f32_dpp v19, v134, v103 row_newbcast:7 row_mask:0xf bank_mask:0xf
	v_fmac_f32_dpp v18, v130, v104 row_newbcast:8 row_mask:0xf bank_mask:0xf
	v_fmac_f32_dpp v19, v134, v104 row_newbcast:8 row_mask:0xf bank_mask:0xf
	v_fmac_f32_dpp v18, v130, v105 row_newbcast:9 row_mask:0xf bank_mask:0xf
	v_fmac_f32_dpp v19, v134, v105 row_newbcast:9 row_mask:0xf bank_mask:0xf
	v_fmac_f32_dpp v18, v130, v106 row_newbcast:10 row_mask:0xf bank_mask:0xf
	v_fmac_f32_dpp v19, v134, v106 row_newbcast:10 row_mask:0xf bank_mask:0xf
	v_fmac_f32_dpp v18, v130, v107 row_newbcast:11 row_mask:0xf bank_mask:0xf
	v_fmac_f32_dpp v19, v134, v107 row_newbcast:11 row_mask:0xf bank_mask:0xf
	v_fmac_f32_dpp v18, v130, v108 row_newbcast:12 row_mask:0xf bank_mask:0xf
	v_fmac_f32_dpp v19, v134, v108 row_newbcast:12 row_mask:0xf bank_mask:0xf
	v_fmac_f32_dpp v18, v130, v109 row_newbcast:13 row_mask:0xf bank_mask:0xf
	v_fmac_f32_dpp v19, v134, v109 row_newbcast:13 row_mask:0xf bank_mask:0xf
	v_fmac_f32_dpp v18, v130, v110 row_newbcast:14 row_mask:0xf bank_mask:0xf
	v_fmac_f32_dpp v19, v134, v110 row_newbcast:14 row_mask:0xf bank_mask:0xf
	v_fmac_f32_dpp v18, v130, v111 row_newbcast:15 row_mask:0xf bank_mask:0xf
	v_fmac_f32_dpp v19, v134, v111 row_newbcast:15 row_mask:0xf bank_mask:0xf
	s_waitcnt vmcnt(0)
	v_fmac_f32_dpp v18, v131, v112 row_newbcast:0 row_mask:0xf bank_mask:0xf
	v_fmac_f32_dpp v19, v135, v112 row_newbcast:0 row_mask:0xf bank_mask:0xf
	v_fmac_f32_dpp v18, v131, v113 row_newbcast:1 row_mask:0xf bank_mask:0xf
	v_fmac_f32_dpp v19, v135, v113 row_newbcast:1 row_mask:0xf bank_mask:0xf
	v_fmac_f32_dpp v18, v131, v114 row_newbcast:2 row_mask:0xf bank_mask:0xf
	v_fmac_f32_dpp v19, v135, v114 row_newbcast:2 row_mask:0xf bank_mask:0xf
	v_fmac_f32_dpp v18, v131, v115 row_newbcast:3 row_mask:0xf bank_mask:0xf
	v_fmac_f32_dpp v19, v135, v115 row_newbcast:3 row_mask:0xf bank_mask:0xf
	v_fmac_f32_dpp v18, v131, v116 row_newbcast:4 row_mask:0xf bank_mask:0xf
	v_fmac_f32_dpp v19, v135, v116 row_newbcast:4 row_mask:0xf bank_mask:0xf
	v_fmac_f32_dpp v18, v131, v117 row_newbcast:5 row_mask:0xf bank_mask:0xf
	v_fmac_f32_dpp v19, v135, v117 row_newbcast:5 row_mask:0xf bank_mask:0xf
	v_fmac_f32_dpp v18, v131, v118 row_newbcast:6 row_mask:0xf bank_mask:0xf
	v_fmac_f32_dpp v19, v135, v118 row_newbcast:6 row_mask:0xf bank_mask:0xf
	v_fmac_f32_dpp v18, v131, v119 row_newbcast:7 row_mask:0xf bank_mask:0xf
	v_fmac_f32_dpp v19, v135, v119 row_newbcast:7 row_mask:0xf bank_mask:0xf
	v_fmac_f32_dpp v18, v131, v120 row_newbcast:8 row_mask:0xf bank_mask:0xf
	v_fmac_f32_dpp v19, v135, v120 row_newbcast:8 row_mask:0xf bank_mask:0xf
	v_fmac_f32_dpp v18, v131, v121 row_newbcast:9 row_mask:0xf bank_mask:0xf
	v_fmac_f32_dpp v19, v135, v121 row_newbcast:9 row_mask:0xf bank_mask:0xf
	v_fmac_f32_dpp v18, v131, v122 row_newbcast:10 row_mask:0xf bank_mask:0xf
	v_fmac_f32_dpp v19, v135, v122 row_newbcast:10 row_mask:0xf bank_mask:0xf
	v_fmac_f32_dpp v18, v131, v123 row_newbcast:11 row_mask:0xf bank_mask:0xf
	v_fmac_f32_dpp v19, v135, v123 row_newbcast:11 row_mask:0xf bank_mask:0xf
	v_fmac_f32_dpp v18, v131, v124 row_newbcast:12 row_mask:0xf bank_mask:0xf
	v_fmac_f32_dpp v19, v135, v124 row_newbcast:12 row_mask:0xf bank_mask:0xf
	v_fmac_f32_dpp v18, v131, v125 row_newbcast:13 row_mask:0xf bank_mask:0xf
	v_fmac_f32_dpp v19, v135, v125 row_newbcast:13 row_mask:0xf bank_mask:0xf
	v_fmac_f32_dpp v18, v131, v126 row_newbcast:14 row_mask:0xf bank_mask:0xf
	v_fmac_f32_dpp v19, v135, v126 row_newbcast:14 row_mask:0xf bank_mask:0xf
	v_fmac_f32_dpp v18, v131, v127 row_newbcast:15 row_mask:0xf bank_mask:0xf
	v_fmac_f32_dpp v19, v135, v127 row_newbcast:15 row_mask:0xf bank_mask:0xf
	v_add_u32_e32 v16, 0, v20
	ds_write_b64 v16, v[18:19] offset:16384
	s_waitcnt lgkmcnt(0)
	s_barrier
	s_and_saveexec_b64 s[22:23], s[4:5]
	s_cbranch_execz .LBB0_15
	s_lshl_b32 s12, s39, 6
	s_and_b32 s12, s12, 0xc0
	v_lshlrev_b64 v[14:15], 10, v[14:15]
	v_or_b32_e32 v18, s12, v2
	v_mov_b32_e32 v19, v9
	v_lshl_add_u64 v[16:17], s[20:21], 0, v[14:15]
	v_lshlrev_b64 v[18:19], 2, v[18:19]
	v_lshl_add_u64 v[16:17], v[16:17], 0, v[18:19]
	global_load_dword v25, v[16:17], off
	ds_read2st64_b32 v[16:17], v21 offset0:64 offset1:66
	ds_read2st64_b32 v[26:27], v21 offset0:68 offset1:70
	ds_read2st64_b32 v[28:29], v21 offset0:72 offset1:74
	ds_read2st64_b32 v[30:31], v21 offset0:76 offset1:78
	v_lshl_add_u64 v[14:15], s[18:19], 0, v[14:15]
	s_waitcnt lgkmcnt(3)
	v_add_f32_e32 v16, 0, v16
	v_add_f32_e32 v16, v16, v17
	s_waitcnt lgkmcnt(2)
	v_add_f32_e32 v16, v16, v26
	v_add_f32_e32 v16, v16, v27
	s_waitcnt lgkmcnt(1)
	v_add_f32_e32 v16, v16, v28
	v_add_f32_e32 v16, v16, v29
	v_lshl_add_u64 v[14:15], v[14:15], 0, v[18:19]
	s_waitcnt lgkmcnt(0)
	v_add_f32_e32 v16, v16, v30
	v_add_co_u32_e32 v14, vcc, 0x80000, v14
	v_add_f32_e32 v16, v16, v31
	s_nop 0
	v_addc_co_u32_e32 v15, vcc, 0, v15, vcc
	s_waitcnt vmcnt(0)
	v_add_f32_e32 v16, v16, v25
	global_store_dword v[14:15], v16, off

.LBB0_20:
	s_or_b64 exec, exec, s[20:21]
	s_mul_hi_i32 s12, s39, 0x38e38e39
	s_lshr_b32 s20, s12, 31
	s_ashr_i32 s12, s12, 5
	s_add_i32 s12, s12, s20
	s_mov_b64 s[20:21], s[0:1]
	s_waitcnt lgkmcnt(0)
	s_barrier
	s_load_dwordx2 s[22:23], s[20:21], 0x18
	s_mul_i32 s24, s12, 0x90
	s_sub_i32 s20, s39, s24
	s_lshl_b32 s20, s20, 6
	s_mul_i32 s24, s12, 0x2400000
	s_mul_hi_i32 s21, s12, 0x2400000
	s_waitcnt lgkmcnt(0)
	s_add_u32 s24, s22, s24
	s_addc_u32 s25, s23, s21
	s_mov_b64 s[22:23], s[0:1]
	s_load_dwordx2 s[22:23], s[22:23], 0x20
	v_lshl_add_u64 v[14:15], s[24:25], 0, v[10:11]
	s_ashr_i32 s21, s20, 31
	v_lshl_add_u64 v[14:15], s[20:21], 2, v[14:15]
	v_mov_b32_e32 v16, 0
	v_lshl_add_u64 v[14:15], v[14:15], 0, v[8:9]
	s_mov_b64 s[24:25], 0
	v_mov_b32_e32 v18, v22
	v_mov_b32_e32 v17, v16
	s_mov_b32 s42, 0x9000
	s_mov_b32 s43, 0
	v_mov_b64_e32 v[136:137], v[14:15]
	v_mbcnt_lo_u32_b32 v139, -1, 0
	v_mbcnt_hi_u32_b32 v139, -1, v139
	v_and_b32_e32 v139, 15, v139
	v_lshl_add_u32 v138, v139, 2, v18
	ds_read_b32 v128, v138
	ds_read_b32 v132, v138 offset:4096
	v_add_u32_e32 v138, 64, v138
	global_load_dword v64, v[136:137], off
	v_lshl_add_u64 v[136:137], v[136:137], 0, s[42:43]
	global_load_dword v65, v[136:137], off
	v_lshl_add_u64 v[136:137], v[136:137], 0, s[42:43]
	global_load_dword v66, v[136:137], off
	v_lshl_add_u64 v[136:137], v[136:137], 0, s[42:43]
	global_load_dword v67, v[136:137], off
	v_lshl_add_u64 v[136:137], v[136:137], 0, s[42:43]
	global_load_dword v68, v[136:137], off
	v_lshl_add_u64 v[136:137], v[136:137], 0, s[42:43]
	global_load_dword v69, v[136:137], off
	v_lshl_add_u64 v[136:137], v[136:137], 0, s[42:43]
	global_load_dword v70, v[136:137], off
	v_lshl_add_u64 v[136:137], v[136:137], 0, s[42:43]
	global_load_dword v71, v[136:137], off
	v_lshl_add_u64 v[136:137], v[136:137], 0, s[42:43]
	global_load_dword v72, v[136:137], off
	v_lshl_add_u64 v[136:137], v[136:137], 0, s[42:43]
	global_load_dword v73, v[136:137], off
	v_lshl_add_u64 v[136:137], v[136:137], 0, s[42:43]
	global_load_dword v74, v[136:137], off
	v_lshl_add_u64 v[136:137], v[136:137], 0, s[42:43]
	global_load_dword v75, v[136:137], off
	v_lshl_add_u64 v[136:137], v[136:137], 0, s[42:43]
	global_load_dword v76, v[136:137], off
	v_lshl_add_u64 v[136:137], v[136:137], 0, s[42:43]
	global_load_dword v77, v[136:137], off
	v_lshl_add_u64 v[136:137], v[136:137], 0, s[42:43]
	global_load_dword v78, v[136:137], off
	v_lshl_add_u64 v[136:137], v[136:137], 0, s[42:43]
	global_load_dword v79, v[136:137], off
	v_lshl_add_u64 v[136:137], v[136:137], 0, s[42:43]
	ds_read_b32 v129, v138
	ds_read_b32 v133, v138 offset:4096
	v_add_u32_e32 v138, 64, v138
	global_load_dword v80, v[136:137], off
	v_lshl_add_u64 v[136:137], v[136:137], 0, s[42:43]
	global_load_dword v81, v[136:137], off
	v_lshl_add_u64 v[136:137], v[136:137], 0, s[42:43]
	global_load_dword v82, v[136:137], off
	v_lshl_add_u64 v[136:137], v[136:137], 0, s[42:43]
	global_load_dword v83, v[136:137], off
	v_lshl_add_u64 v[136:137], v[136:137], 0, s[42:43]
	global_load_dword v84, v[136:137], off
	v_lshl_add_u64 v[136:137], v[136:137], 0, s[42:43]
	global_load_dword v85, v[136:137], off
	v_lshl_add_u64 v[136:137], v[136:137], 0, s[42:43]
	global_load_dword v86, v[136:137], off
	v_lshl_add_u64 v[136:137], v[136:137], 0, s[42:43]
	global_load_dword v87, v[136:137], off
	v_lshl_add_u64 v[136:137], v[136:137], 0, s[42:43]
	global_load_dword v88, v[136:137], off
	v_lshl_add_u64 v[136:137], v[136:137], 0, s[42:43]
	global_load_dword v89, v[136:137], off
	v_lshl_add_u64 v[136:137], v[136:137], 0, s[42:43]
	global_load_dword v90, v[136:137], off
	v_lshl_add_u64 v[136:137], v[136:137], 0, s[42:43]
	global_load_dword v91, v[136:137], off
	v_lshl_add_u64 v[136:137], v[136:137], 0, s[42:43]
	global_load_dword v92, v[136:137], off
	v_lshl_add_u64 v[136:137], v[136:137], 0, s[42:43]
	global_load_dword v93, v[136:137], off
	v_lshl_add_u64 v[136:137], v[136:137], 0, s[42:43]
	global_load_dword v94, v[136:137], off
	v_lshl_add_u64 v[136:137], v[136:137], 0, s[42:43]
	global_load_dword v95, v[136:137], off
	v_lshl_add_u64 v[136:137], v[136:137], 0, s[42:43]
	ds_read_b32 v130, v138
	ds_read_b32 v134, v138 offset:4096
	v_add_u32_e32 v138, 64, v138
	global_load_dword v96, v[136:137], off
	v_lshl_add_u64 v[136:137], v[136:137], 0, s[42:43]
	global_load_dword v97, v[136:137], off
	v_lshl_add_u64 v[136:137], v[136:137], 0, s[42:43]
	global_load_dword v98, v[136:137], off
	v_lshl_add_u64 v[136:137], v[136:137], 0, s[42:43]
	global_load_dword v99, v[136:137], off
	v_lshl_add_u64 v[136:137], v[136:137], 0, s[42:43]
	global_load_dword v100, v[136:137], off
	v_lshl_add_u64 v[136:137], v[136:137], 0, s[42:43]
	global_load_dword v101, v[136:137], off
	v_lshl_add_u64 v[136:137], v[136:137], 0, s[42:43]
	global_load_dword v102, v[136:137], off
	v_lshl_add_u64 v[136:137], v[136:137], 0, s[42:43]
	global_load_dword v103, v[136:137], off
	v_lshl_add_u64 v[136:137], v[136:137], 0, s[42:43]
	global_load_dword v104, v[136:137], off
	v_lshl_add_u64 v[136:137], v[136:137], 0, s[42:43]
	global_load_dword v105, v[136:137], off
	v_lshl_add_u64 v[136:137], v[136:137], 0, s[42:43]
	global_load_dword v106, v[136:137], off
	v_lshl_add_u64 v[136:137], v[136:137], 0, s[42:43]
	global_load_dword v107, v[136:137], off
	v_lshl_add_u64 v[136:137], v[136:137], 0, s[42:43]
	global_load_dword v108, v[136:137], off
	v_lshl_add_u64 v[136:137], v[136:137], 0, s[42:43]
	global_load_dword v109, v[136:137], off
	v_lshl_add_u64 v[136:137], v[136:137], 0, s[42:43]
	global_load_dword v110, v[136:137], off
	v_lshl_add_u64 v[136:137], v[136:137], 0, s[42:43]
	global_load_dword v111, v[136:137], off
	v_lshl_add_u64 v[136:137], v[136:137], 0, s[42:43]
	s_mov_b32 s44, 0
pgv_b_loop:
	s_waitcnt vmcnt(32) lgkmcnt(0)
	ds_read_b32 v131, v138
	ds_read_b32 v135, v138 offset:4096
	v_add_u32_e32 v138, 64, v138
	global_load_dword v112, v[136:137], off
	v_lshl_add_u64 v[136:137], v[136:137], 0, s[42:43]
	global_load_dword v113, v[136:137], off
	v_lshl_add_u64 v[136:137], v[136:137], 0, s[42:43]
	global_load_dword v114, v[136:137], off
	v_lshl_add_u64 v[136:137], v[136:137], 0, s[42:43]
	global_load_dword v115, v[136:137], off
	v_lshl_add_u64 v[136:137], v[136:137], 0, s[42:43]
	global_load_dword v116, v[136:137], off
	v_lshl_add_u64 v[136:137], v[136:137], 0, s[42:43]
	global_load_dword v117, v[136:137], off
	v_lshl_add_u64 v[136:137], v[136:137], 0, s[42:43]
	global_load_dword v118, v[136:137], off
	v_lshl_add_u64 v[136:137], v[136:137], 0, s[42:43]
	global_load_dword v119, v[136:137], off
	v_lshl_add_u64 v[136:137], v[136:137], 0, s[42:43]
	global_load_dword v120, v[136:137], off
	v_lshl_add_u64 v[136:137], v[136:137], 0, s[42:43]
	global_load_dword v121, v[136:137], off
	v_lshl_add_u64 v[136:137], v[136:137], 0, s[42:43]
	global_load_dword v122, v[136:137], off
	v_lshl_add_u64 v[136:137], v[136:137], 0, s[42:43]
	global_load_dword v123, v[136:137], off
	v_lshl_add_u64 v[136:137], v[136:137], 0, s[42:43]
	global_load_dword v124, v[136:137], off
	v_lshl_add_u64 v[136:137], v[136:137], 0, s[42:43]
	global_load_dword v125, v[136:137], off
	v_lshl_add_u64 v[136:137], v[136:137], 0, s[42:43]
	global_load_dword v126, v[136:137], off
	v_lshl_add_u64 v[136:137], v[136:137], 0, s[42:43]
	global_load_dword v127, v[136:137], off
	v_lshl_add_u64 v[136:137], v[136:137], 0, s[42:43]
	v_fmac_f32_dpp v16, v128, v64 row_newbcast:0 row_mask:0xf bank_mask:0xf
	v_fmac_f32_dpp v17, v132, v64 row_newbcast:0 row_mask:0xf bank_mask:0xf
	v_fmac_f32_dpp v16, v128, v65 row_newbcast:1 row_mask:0xf bank_mask:0xf
	v_fmac_f32_dpp v17, v132, v65 row_newbcast:1 row_mask:0xf bank_mask:0xf
	v_fmac_f32_dpp v16, v128, v66 row_newbcast:2 row_mask:0xf bank_mask:0xf
	v_fmac_f32_dpp v17, v132, v66 row_newbcast:2 row_mask:0xf bank_mask:0xf
	v_fmac_f32_dpp v16, v128, v67 row_newbcast:3 row_mask:0xf bank_mask:0xf
	v_fmac_f32_dpp v17, v132, v67 row_newbcast:3 row_mask:0xf bank_mask:0xf
	v_fmac_f32_dpp v16, v128, v68 row_newbcast:4 row_mask:0xf bank_mask:0xf
	v_fmac_f32_dpp v17, v132, v68 row_newbcast:4 row_mask:0xf bank_mask:0xf
	v_fmac_f32_dpp v16, v128, v69 row_newbcast:5 row_mask:0xf bank_mask:0xf
	v_fmac_f32_dpp v17, v132, v69 row_newbcast:5 row_mask:0xf bank_mask:0xf
	v_fmac_f32_dpp v16, v128, v70 row_newbcast:6 row_mask:0xf bank_mask:0xf
	v_fmac_f32_dpp v17, v132, v70 row_newbcast:6 row_mask:0xf bank_mask:0xf
	v_fmac_f32_dpp v16, v128, v71 row_newbcast:7 row_mask:0xf bank_mask:0xf
	v_fmac_f32_dpp v17, v132, v71 row_newbcast:7 row_mask:0xf bank_mask:0xf
	v_fmac_f32_dpp v16, v128, v72 row_newbcast:8 row_mask:0xf bank_mask:0xf
	v_fmac_f32_dpp v17, v132, v72 row_newbcast:8 row_mask:0xf bank_mask:0xf
	v_fmac_f32_dpp v16, v128, v73 row_newbcast:9 row_mask:0xf bank_mask:0xf
	v_fmac_f32_dpp v17, v132, v73 row_newbcast:9 row_mask:0xf bank_mask:0xf
	v_fmac_f32_dpp v16, v128, v74 row_newbcast:10 row_mask:0xf bank_mask:0xf
	v_fmac_f32_dpp v17, v132, v74 row_newbcast:10 row_mask:0xf bank_mask:0xf
	v_fmac_f32_dpp v16, v128, v75 row_newbcast:11 row_mask:0xf bank_mask:0xf
	v_fmac_f32_dpp v17, v132, v75 row_newbcast:11 row_mask:0xf bank_mask:0xf
	v_fmac_f32_dpp v16, v128, v76 row_newbcast:12 row_mask:0xf bank_mask:0xf
	v_fmac_f32_dpp v17, v132, v76 row_newbcast:12 row_mask:0xf bank_mask:0xf
	v_fmac_f32_dpp v16, v128, v77 row_newbcast:13 row_mask:0xf bank_mask:0xf
	v_fmac_f32_dpp v17, v132, v77 row_newbcast:13 row_mask:0xf bank_mask:0xf
	v_fmac_f32_dpp v16, v128, v78 row_newbcast:14 row_mask:0xf bank_mask:0xf
	v_fmac_f32_dpp v17, v132, v78 row_newbcast:14 row_mask:0xf bank_mask:0xf
	v_fmac_f32_dpp v16, v128, v79 row_newbcast:15 row_mask:0xf bank_mask:0xf
	v_fmac_f32_dpp v17, v132, v79 row_newbcast:15 row_mask:0xf bank_mask:0xf
	s_waitcnt vmcnt(32) lgkmcnt(0)
	ds_read_b32 v128, v138
	ds_read_b32 v132, v138 offset:4096
	v_add_u32_e32 v138, 64, v138
	global_load_dword v64, v[136:137], off
	v_lshl_add_u64 v[136:137], v[136:137], 0, s[42:43]
	global_load_dword v65, v[136:137], off
	v_lshl_add_u64 v[136:137], v[136:137], 0, s[42:43]
	global_load_dword v66, v[136:137], off
	v_lshl_add_u64 v[136:137], v[136:137], 0, s[42:43]
	global_load_dword v67, v[136:137], off
	v_lshl_add_u64 v[136:137], v[136:137], 0, s[42:43]
	global_load_dword v68, v[136:137], off
	v_lshl_add_u64 v[136:137], v[136:137], 0, s[42:43]
	global_load_dword v69, v[136:137], off
	v_lshl_add_u64 v[136:137], v[136:137], 0, s[42:43]
	global_load_dword v70, v[136:137], off
	v_lshl_add_u64 v[136:137], v[136:137], 0, s[42:43]
	global_load_dword v71, v[136:137], off
	v_lshl_add_u64 v[136:137], v[136:137], 0, s[42:43]
	global_load_dword v72, v[136:137], off
	v_lshl_add_u64 v[136:137], v[136:137], 0, s[42:43]
	global_load_dword v73, v[136:137], off
	v_lshl_add_u64 v[136:137], v[136:137], 0, s[42:43]
	global_load_dword v74, v[136:137], off
	v_lshl_add_u64 v[136:137], v[136:137], 0, s[42:43]
	global_load_dword v75, v[136:137], off
	v_lshl_add_u64 v[136:137], v[136:137], 0, s[42:43]
	global_load_dword v76, v[136:137], off
	v_lshl_add_u64 v[136:137], v[136:137], 0, s[42:43]
	global_load_dword v77, v[136:137], off
	v_lshl_add_u64 v[136:137], v[136:137], 0, s[42:43]
	global_load_dword v78, v[136:137], off
	v_lshl_add_u64 v[136:137], v[136:137], 0, s[42:43]
	global_load_dword v79, v[136:137], off
	v_lshl_add_u64 v[136:137], v[136:137], 0, s[42:43]
	v_fmac_f32_dpp v16, v129, v80 row_newbcast:0 row_mask:0xf bank_mask:0xf
	v_fmac_f32_dpp v17, v133, v80 row_newbcast:0 row_mask:0xf bank_mask:0xf
	v_fmac_f32_dpp v16, v129, v81 row_newbcast:1 row_mask:0xf bank_mask:0xf
	v_fmac_f32_dpp v17, v133, v81 row_newbcast:1 row_mask:0xf bank_mask:0xf
	v_fmac_f32_dpp v16, v129, v82 row_newbcast:2 row_mask:0xf bank_mask:0xf
	v_fmac_f32_dpp v17, v133, v82 row_newbcast:2 row_mask:0xf bank_mask:0xf
	v_fmac_f32_dpp v16, v129, v83 row_newbcast:3 row_mask:0xf bank_mask:0xf
	v_fmac_f32_dpp v17, v133, v83 row_newbcast:3 row_mask:0xf bank_mask:0xf
	v_fmac_f32_dpp v16, v129, v84 row_newbcast:4 row_mask:0xf bank_mask:0xf
	v_fmac_f32_dpp v17, v133, v84 row_newbcast:4 row_mask:0xf bank_mask:0xf
	v_fmac_f32_dpp v16, v129, v85 row_newbcast:5 row_mask:0xf bank_mask:0xf
	v_fmac_f32_dpp v17, v133, v85 row_newbcast:5 row_mask:0xf bank_mask:0xf
	v_fmac_f32_dpp v16, v129, v86 row_newbcast:6 row_mask:0xf bank_mask:0xf
	v_fmac_f32_dpp v17, v133, v86 row_newbcast:6 row_mask:0xf bank_mask:0xf
	v_fmac_f32_dpp v16, v129, v87 row_newbcast:7 row_mask:0xf bank_mask:0xf
	v_fmac_f32_dpp v17, v133, v87 row_newbcast:7 row_mask:0xf bank_mask:0xf
	v_fmac_f32_dpp v16, v129, v88 row_newbcast:8 row_mask:0xf bank_mask:0xf
	v_fmac_f32_dpp v17, v133, v88 row_newbcast:8 row_mask:0xf bank_mask:0xf
	v_fmac_f32_dpp v16, v129, v89 row_newbcast:9 row_mask:0xf bank_mask:0xf
	v_fmac_f32_dpp v17, v133, v89 row_newbcast:9 row_mask:0xf bank_mask:0xf
	v_fmac_f32_dpp v16, v129, v90 row_newbcast:10 row_mask:0xf bank_mask:0xf
	v_fmac_f32_dpp v17, v133, v90 row_newbcast:10 row_mask:0xf bank_mask:0xf
	v_fmac_f32_dpp v16, v129, v91 row_newbcast:11 row_mask:0xf bank_mask:0xf
	v_fmac_f32_dpp v17, v133, v91 row_newbcast:11 row_mask:0xf bank_mask:0xf
	v_fmac_f32_dpp v16, v129, v92 row_newbcast:12 row_mask:0xf bank_mask:0xf
	v_fmac_f32_dpp v17, v133, v92 row_newbcast:12 row_mask:0xf bank_mask:0xf
	v_fmac_f32_dpp v16, v129, v93 row_newbcast:13 row_mask:0xf bank_mask:0xf
	v_fmac_f32_dpp v17, v133, v93 row_newbcast:13 row_mask:0xf bank_mask:0xf
	v_fmac_f32_dpp v16, v129, v94 row_newbcast:14 row_mask:0xf bank_mask:0xf
	v_fmac_f32_dpp v17, v133, v94 row_newbcast:14 row_mask:0xf bank_mask:0xf
	v_fmac_f32_dpp v16, v129, v95 row_newbcast:15 row_mask:0xf bank_mask:0xf
	v_fmac_f32_dpp v17, v133, v95 row_newbcast:15 row_mask:0xf bank_mask:0xf
	s_waitcnt vmcnt(32) lgkmcnt(0)
	ds_read_b32 v129, v138
	ds_read_b32 v133, v138 offset:4096
	v_add_u32_e32 v138, 64, v138
	global_load_dword v80, v[136:137], off
	v_lshl_add_u64 v[136:137], v[136:137], 0, s[42:43]
	global_load_dword v81, v[136:137], off
	v_lshl_add_u64 v[136:137], v[136:137], 0, s[42:43]
	global_load_dword v82, v[136:137], off
	v_lshl_add_u64 v[136:137], v[136:137], 0, s[42:43]
	global_load_dword v83, v[136:137], off
	v_lshl_add_u64 v[136:137], v[136:137], 0, s[42:43]
	global_load_dword v84, v[136:137], off
	v_lshl_add_u64 v[136:137], v[136:137], 0, s[42:43]
	global_load_dword v85, v[136:137], off
	v_lshl_add_u64 v[136:137], v[136:137], 0, s[42:43]
	global_load_dword v86, v[136:137], off
	v_lshl_add_u64 v[136:137], v[136:137], 0, s[42:43]
	global_load_dword v87, v[136:137], off
	v_lshl_add_u64 v[136:137], v[136:137], 0, s[42:43]
	global_load_dword v88, v[136:137], off
	v_lshl_add_u64 v[136:137], v[136:137], 0, s[42:43]
	global_load_dword v89, v[136:137], off
	v_lshl_add_u64 v[136:137], v[136:137], 0, s[42:43]
	global_load_dword v90, v[136:137], off
	v_lshl_add_u64 v[136:137], v[136:137], 0, s[42:43]
	global_load_dword v91, v[136:137], off
	v_lshl_add_u64 v[136:137], v[136:137], 0, s[42:43]
	global_load_dword v92, v[136:137], off
	v_lshl_add_u64 v[136:137], v[136:137], 0, s[42:43]
	global_load_dword v93, v[136:137], off
	v_lshl_add_u64 v[136:137], v[136:137], 0, s[42:43]
	global_load_dword v94, v[136:137], off
	v_lshl_add_u64 v[136:137], v[136:137], 0, s[42:43]
	global_load_dword v95, v[136:137], off
	v_lshl_add_u64 v[136:137], v[136:137], 0, s[42:43]
	v_fmac_f32_dpp v16, v130, v96 row_newbcast:0 row_mask:0xf bank_mask:0xf
	v_fmac_f32_dpp v17, v134, v96 row_newbcast:0 row_mask:0xf bank_mask:0xf
	v_fmac_f32_dpp v16, v130, v97 row_newbcast:1 row_mask:0xf bank_mask:0xf
	v_fmac_f32_dpp v17, v134, v97 row_newbcast:1 row_mask:0xf bank_mask:0xf
	v_fmac_f32_dpp v16, v130, v98 row_newbcast:2 row_mask:0xf bank_mask:0xf
	v_fmac_f32_dpp v17, v134, v98 row_newbcast:2 row_mask:0xf bank_mask:0xf
	v_fmac_f32_dpp v16, v130, v99 row_newbcast:3 row_mask:0xf bank_mask:0xf
	v_fmac_f32_dpp v17, v134, v99 row_newbcast:3 row_mask:0xf bank_mask:0xf
	v_fmac_f32_dpp v16, v130, v100 row_newbcast:4 row_mask:0xf bank_mask:0xf
	v_fmac_f32_dpp v17, v134, v100 row_newbcast:4 row_mask:0xf bank_mask:0xf
	v_fmac_f32_dpp v16, v130, v101 row_newbcast:5 row_mask:0xf bank_mask:0xf
	v_fmac_f32_dpp v17, v134, v101 row_newbcast:5 row_mask:0xf bank_mask:0xf
	v_fmac_f32_dpp v16, v130, v102 row_newbcast:6 row_mask:0xf bank_mask:0xf
	v_fmac_f32_dpp v17, v134, v102 row_newbcast:6 row_mask:0xf bank_mask:0xf
	v_fmac_f32_dpp v16, v130, v103 row_newbcast:7 row_mask:0xf bank_mask:0xf
	v_fmac_f32_dpp v17, v134, v103 row_newbcast:7 row_mask:0xf bank_mask:0xf
	v_fmac_f32_dpp v16, v130, v104 row_newbcast:8 row_mask:0xf bank_mask:0xf
	v_fmac_f32_dpp v17, v134, v104 row_newbcast:8 row_mask:0xf bank_mask:0xf
	v_fmac_f32_dpp v16, v130, v105 row_newbcast:9 row_mask:0xf bank_mask:0xf
	v_fmac_f32_dpp v17, v134, v105 row_newbcast:9 row_mask:0xf bank_mask:0xf
	v_fmac_f32_dpp v16, v130, v106 row_newbcast:10 row_mask:0xf bank_mask:0xf
	v_fmac_f32_dpp v17, v134, v106 row_newbcast:10 row_mask:0xf bank_mask:0xf
	v_fmac_f32_dpp v16, v130, v107 row_newbcast:11 row_mask:0xf bank_mask:0xf
	v_fmac_f32_dpp v17, v134, v107 row_newbcast:11 row_mask:0xf bank_mask:0xf
	v_fmac_f32_dpp v16, v130, v108 row_newbcast:12 row_mask:0xf bank_mask:0xf
	v_fmac_f32_dpp v17, v134, v108 row_newbcast:12 row_mask:0xf bank_mask:0xf
	v_fmac_f32_dpp v16, v130, v109 row_newbcast:13 row_mask:0xf bank_mask:0xf
	v_fmac_f32_dpp v17, v134, v109 row_newbcast:13 row_mask:0xf bank_mask:0xf
	v_fmac_f32_dpp v16, v130, v110 row_newbcast:14 row_mask:0xf bank_mask:0xf
	v_fmac_f32_dpp v17, v134, v110 row_newbcast:14 row_mask:0xf bank_mask:0xf
	v_fmac_f32_dpp v16, v130, v111 row_newbcast:15 row_mask:0xf bank_mask:0xf
	v_fmac_f32_dpp v17, v134, v111 row_newbcast:15 row_mask:0xf bank_mask:0xf
	s_waitcnt vmcnt(32) lgkmcnt(0)
	ds_read_b32 v130, v138
	ds_read_b32 v134, v138 offset:4096
	v_add_u32_e32 v138, 64, v138
	global_load_dword v96, v[136:137], off
	v_lshl_add_u64 v[136:137], v[136:137], 0, s[42:43]
	global_load_dword v97, v[136:137], off
	v_lshl_add_u64 v[136:137], v[136:137], 0, s[42:43]
	global_load_dword v98, v[136:137], off
	v_lshl_add_u64 v[136:137], v[136:137], 0, s[42:43]
	global_load_dword v99, v[136:137], off
	v_lshl_add_u64 v[136:137], v[136:137], 0, s[42:43]
	global_load_dword v100, v[136:137], off
	v_lshl_add_u64 v[136:137], v[136:137], 0, s[42:43]
	global_load_dword v101, v[136:137], off
	v_lshl_add_u64 v[136:137], v[136:137], 0, s[42:43]
	global_load_dword v102, v[136:137], off
	v_lshl_add_u64 v[136:137], v[136:137], 0, s[42:43]
	global_load_dword v103, v[136:137], off
	v_lshl_add_u64 v[136:137], v[136:137], 0, s[42:43]
	global_load_dword v104, v[136:137], off
	v_lshl_add_u64 v[136:137], v[136:137], 0, s[42:43]
	global_load_dword v105, v[136:137], off
	v_lshl_add_u64 v[136:137], v[136:137], 0, s[42:43]
	global_load_dword v106, v[136:137], off
	v_lshl_add_u64 v[136:137], v[136:137], 0, s[42:43]
	global_load_dword v107, v[136:137], off
	v_lshl_add_u64 v[136:137], v[136:137], 0, s[42:43]
	global_load_dword v108, v[136:137], off
	v_lshl_add_u64 v[136:137], v[136:137], 0, s[42:43]
	global_load_dword v109, v[136:137], off
	v_lshl_add_u64 v[136:137], v[136:137], 0, s[42:43]
	global_load_dword v110, v[136:137], off
	v_lshl_add_u64 v[136:137], v[136:137], 0, s[42:43]
	global_load_dword v111, v[136:137], off
	v_lshl_add_u64 v[136:137], v[136:137], 0, s[42:43]
	v_fmac_f32_dpp v16, v131, v112 row_newbcast:0 row_mask:0xf bank_mask:0xf
	v_fmac_f32_dpp v17, v135, v112 row_newbcast:0 row_mask:0xf bank_mask:0xf
	v_fmac_f32_dpp v16, v131, v113 row_newbcast:1 row_mask:0xf bank_mask:0xf
	v_fmac_f32_dpp v17, v135, v113 row_newbcast:1 row_mask:0xf bank_mask:0xf
	v_fmac_f32_dpp v16, v131, v114 row_newbcast:2 row_mask:0xf bank_mask:0xf
	v_fmac_f32_dpp v17, v135, v114 row_newbcast:2 row_mask:0xf bank_mask:0xf
	v_fmac_f32_dpp v16, v131, v115 row_newbcast:3 row_mask:0xf bank_mask:0xf
	v_fmac_f32_dpp v17, v135, v115 row_newbcast:3 row_mask:0xf bank_mask:0xf
	v_fmac_f32_dpp v16, v131, v116 row_newbcast:4 row_mask:0xf bank_mask:0xf
	v_fmac_f32_dpp v17, v135, v116 row_newbcast:4 row_mask:0xf bank_mask:0xf
	v_fmac_f32_dpp v16, v131, v117 row_newbcast:5 row_mask:0xf bank_mask:0xf
	v_fmac_f32_dpp v17, v135, v117 row_newbcast:5 row_mask:0xf bank_mask:0xf
	v_fmac_f32_dpp v16, v131, v118 row_newbcast:6 row_mask:0xf bank_mask:0xf
	v_fmac_f32_dpp v17, v135, v118 row_newbcast:6 row_mask:0xf bank_mask:0xf
	v_fmac_f32_dpp v16, v131, v119 row_newbcast:7 row_mask:0xf bank_mask:0xf
	v_fmac_f32_dpp v17, v135, v119 row_newbcast:7 row_mask:0xf bank_mask:0xf
	v_fmac_f32_dpp v16, v131, v120 row_newbcast:8 row_mask:0xf bank_mask:0xf
	v_fmac_f32_dpp v17, v135, v120 row_newbcast:8 row_mask:0xf bank_mask:0xf
	v_fmac_f32_dpp v16, v131, v121 row_newbcast:9 row_mask:0xf bank_mask:0xf
	v_fmac_f32_dpp v17, v135, v121 row_newbcast:9 row_mask:0xf bank_mask:0xf
	v_fmac_f32_dpp v16, v131, v122 row_newbcast:10 row_mask:0xf bank_mask:0xf
	v_fmac_f32_dpp v17, v135, v122 row_newbcast:10 row_mask:0xf bank_mask:0xf
	v_fmac_f32_dpp v16, v131, v123 row_newbcast:11 row_mask:0xf bank_mask:0xf
	v_fmac_f32_dpp v17, v135, v123 row_newbcast:11 row_mask:0xf bank_mask:0xf
	v_fmac_f32_dpp v16, v131, v124 row_newbcast:12 row_mask:0xf bank_mask:0xf
	v_fmac_f32_dpp v17, v135, v124 row_newbcast:12 row_mask:0xf bank_mask:0xf
	v_fmac_f32_dpp v16, v131, v125 row_newbcast:13 row_mask:0xf bank_mask:0xf
	v_fmac_f32_dpp v17, v135, v125 row_newbcast:13 row_mask:0xf bank_mask:0xf
	v_fmac_f32_dpp v16, v131, v126 row_newbcast:14 row_mask:0xf bank_mask:0xf
	v_fmac_f32_dpp v17, v135, v126 row_newbcast:14 row_mask:0xf bank_mask:0xf
	v_fmac_f32_dpp v16, v131, v127 row_newbcast:15 row_mask:0xf bank_mask:0xf
	v_fmac_f32_dpp v17, v135, v127 row_newbcast:15 row_mask:0xf bank_mask:0xf
	s_add_i32 s44, s44, 1
	s_cmp_lt_u32 s44, 1
	s_cbranch_scc1 pgv_b_loop
	s_waitcnt vmcnt(32) lgkmcnt(0)
	ds_read_b32 v131, v138
	ds_read_b32 v135, v138 offset:4096
	v_add_u32_e32 v138, 64, v138
	global_load_dword v112, v[136:137], off
	v_lshl_add_u64 v[136:137], v[136:137], 0, s[42:43]
	global_load_dword v113, v[136:137], off
	v_lshl_add_u64 v[136:137], v[136:137], 0, s[42:43]
	global_load_dword v114, v[136:137], off
	v_lshl_add_u64 v[136:137], v[136:137], 0, s[42:43]
	global_load_dword v115, v[136:137], off
	v_lshl_add_u64 v[136:137], v[136:137], 0, s[42:43]
	global_load_dword v116, v[136:137], off
	v_lshl_add_u64 v[136:137], v[136:137], 0, s[42:43]
	global_load_dword v117, v[136:137], off
	v_lshl_add_u64 v[136:137], v[136:137], 0, s[42:43]
	global_load_dword v118, v[136:137], off
	v_lshl_add_u64 v[136:137], v[136:137], 0, s[42:43]
	global_load_dword v119, v[136:137], off
	v_lshl_add_u64 v[136:137], v[136:137], 0, s[42:43]
	global_load_dword v120, v[136:137], off
	v_lshl_add_u64 v[136:137], v[136:137], 0, s[42:43]
	global_load_dword v121, v[136:137], off
	v_lshl_add_u64 v[136:137], v[136:137], 0, s[42:43]
	global_load_dword v122, v[136:137], off
	v_lshl_add_u64 v[136:137], v[136:137], 0, s[42:43]
	global_load_dword v123, v[136:137], off
	v_lshl_add_u64 v[136:137], v[136:137], 0, s[42:43]
	global_load_dword v124, v[136:137], off
	v_lshl_add_u64 v[136:137], v[136:137], 0, s[42:43]
	global_load_dword v125, v[136:137], off
	v_lshl_add_u64 v[136:137], v[136:137], 0, s[42:43]
	global_load_dword v126, v[136:137], off
	v_lshl_add_u64 v[136:137], v[136:137], 0, s[42:43]
	global_load_dword v127, v[136:137], off
	v_lshl_add_u64 v[136:137], v[136:137], 0, s[42:43]
	v_fmac_f32_dpp v16, v128, v64 row_newbcast:0 row_mask:0xf bank_mask:0xf
	v_fmac_f32_dpp v17, v132, v64 row_newbcast:0 row_mask:0xf bank_mask:0xf
	v_fmac_f32_dpp v16, v128, v65 row_newbcast:1 row_mask:0xf bank_mask:0xf
	v_fmac_f32_dpp v17, v132, v65 row_newbcast:1 row_mask:0xf bank_mask:0xf
	v_fmac_f32_dpp v16, v128, v66 row_newbcast:2 row_mask:0xf bank_mask:0xf
	v_fmac_f32_dpp v17, v132, v66 row_newbcast:2 row_mask:0xf bank_mask:0xf
	v_fmac_f32_dpp v16, v128, v67 row_newbcast:3 row_mask:0xf bank_mask:0xf
	v_fmac_f32_dpp v17, v132, v67 row_newbcast:3 row_mask:0xf bank_mask:0xf
	v_fmac_f32_dpp v16, v128, v68 row_newbcast:4 row_mask:0xf bank_mask:0xf
	v_fmac_f32_dpp v17, v132, v68 row_newbcast:4 row_mask:0xf bank_mask:0xf
	v_fmac_f32_dpp v16, v128, v69 row_newbcast:5 row_mask:0xf bank_mask:0xf
	v_fmac_f32_dpp v17, v132, v69 row_newbcast:5 row_mask:0xf bank_mask:0xf
	v_fmac_f32_dpp v16, v128, v70 row_newbcast:6 row_mask:0xf bank_mask:0xf
	v_fmac_f32_dpp v17, v132, v70 row_newbcast:6 row_mask:0xf bank_mask:0xf
	v_fmac_f32_dpp v16, v128, v71 row_newbcast:7 row_mask:0xf bank_mask:0xf
	v_fmac_f32_dpp v17, v132, v71 row_newbcast:7 row_mask:0xf bank_mask:0xf
	v_fmac_f32_dpp v16, v128, v72 row_newbcast:8 row_mask:0xf bank_mask:0xf
	v_fmac_f32_dpp v17, v132, v72 row_newbcast:8 row_mask:0xf bank_mask:0xf
	v_fmac_f32_dpp v16, v128, v73 row_newbcast:9 row_mask:0xf bank_mask:0xf
	v_fmac_f32_dpp v17, v132, v73 row_newbcast:9 row_mask:0xf bank_mask:0xf
	v_fmac_f32_dpp v16, v128, v74 row_newbcast:10 row_mask:0xf bank_mask:0xf
	v_fmac_f32_dpp v17, v132, v74 row_newbcast:10 row_mask:0xf bank_mask:0xf
	v_fmac_f32_dpp v16, v128, v75 row_newbcast:11 row_mask:0xf bank_mask:0xf
	v_fmac_f32_dpp v17, v132, v75 row_newbcast:11 row_mask:0xf bank_mask:0xf
	v_fmac_f32_dpp v16, v128, v76 row_newbcast:12 row_mask:0xf bank_mask:0xf
	v_fmac_f32_dpp v17, v132, v76 row_newbcast:12 row_mask:0xf bank_mask:0xf
	v_fmac_f32_dpp v16, v128, v77 row_newbcast:13 row_mask:0xf bank_mask:0xf
	v_fmac_f32_dpp v17, v132, v77 row_newbcast:13 row_mask:0xf bank_mask:0xf
	v_fmac_f32_dpp v16, v128, v78 row_newbcast:14 row_mask:0xf bank_mask:0xf
	v_fmac_f32_dpp v17, v132, v78 row_newbcast:14 row_mask:0xf bank_mask:0xf
	v_fmac_f32_dpp v16, v128, v79 row_newbcast:15 row_mask:0xf bank_mask:0xf
	v_fmac_f32_dpp v17, v132, v79 row_newbcast:15 row_mask:0xf bank_mask:0xf
	s_waitcnt vmcnt(32) lgkmcnt(0)
	v_fmac_f32_dpp v16, v129, v80 row_newbcast:0 row_mask:0xf bank_mask:0xf
	v_fmac_f32_dpp v17, v133, v80 row_newbcast:0 row_mask:0xf bank_mask:0xf
	v_fmac_f32_dpp v16, v129, v81 row_newbcast:1 row_mask:0xf bank_mask:0xf
	v_fmac_f32_dpp v17, v133, v81 row_newbcast:1 row_mask:0xf bank_mask:0xf
	v_fmac_f32_dpp v16, v129, v82 row_newbcast:2 row_mask:0xf bank_mask:0xf
	v_fmac_f32_dpp v17, v133, v82 row_newbcast:2 row_mask:0xf bank_mask:0xf
	v_fmac_f32_dpp v16, v129, v83 row_newbcast:3 row_mask:0xf bank_mask:0xf
	v_fmac_f32_dpp v17, v133, v83 row_newbcast:3 row_mask:0xf bank_mask:0xf
	v_fmac_f32_dpp v16, v129, v84 row_newbcast:4 row_mask:0xf bank_mask:0xf
	v_fmac_f32_dpp v17, v133, v84 row_newbcast:4 row_mask:0xf bank_mask:0xf
	v_fmac_f32_dpp v16, v129, v85 row_newbcast:5 row_mask:0xf bank_mask:0xf
	v_fmac_f32_dpp v17, v133, v85 row_newbcast:5 row_mask:0xf bank_mask:0xf
	v_fmac_f32_dpp v16, v129, v86 row_newbcast:6 row_mask:0xf bank_mask:0xf
	v_fmac_f32_dpp v17, v133, v86 row_newbcast:6 row_mask:0xf bank_mask:0xf
	v_fmac_f32_dpp v16, v129, v87 row_newbcast:7 row_mask:0xf bank_mask:0xf
	v_fmac_f32_dpp v17, v133, v87 row_newbcast:7 row_mask:0xf bank_mask:0xf
	v_fmac_f32_dpp v16, v129, v88 row_newbcast:8 row_mask:0xf bank_mask:0xf
	v_fmac_f32_dpp v17, v133, v88 row_newbcast:8 row_mask:0xf bank_mask:0xf
	v_fmac_f32_dpp v16, v129, v89 row_newbcast:9 row_mask:0xf bank_mask:0xf
	v_fmac_f32_dpp v17, v133, v89 row_newbcast:9 row_mask:0xf bank_mask:0xf
	v_fmac_f32_dpp v16, v129, v90 row_newbcast:10 row_mask:0xf bank_mask:0xf
	v_fmac_f32_dpp v17, v133, v90 row_newbcast:10 row_mask:0xf bank_mask:0xf
	v_fmac_f32_dpp v16, v129, v91 row_newbcast:11 row_mask:0xf bank_mask:0xf
	v_fmac_f32_dpp v17, v133, v91 row_newbcast:11 row_mask:0xf bank_mask:0xf
	v_fmac_f32_dpp v16, v129, v92 row_newbcast:12 row_mask:0xf bank_mask:0xf
	v_fmac_f32_dpp v17, v133, v92 row_newbcast:12 row_mask:0xf bank_mask:0xf
	v_fmac_f32_dpp v16, v129, v93 row_newbcast:13 row_mask:0xf bank_mask:0xf
	v_fmac_f32_dpp v17, v133, v93 row_newbcast:13 row_mask:0xf bank_mask:0xf
	v_fmac_f32_dpp v16, v129, v94 row_newbcast:14 row_mask:0xf bank_mask:0xf
	v_fmac_f32_dpp v17, v133, v94 row_newbcast:14 row_mask:0xf bank_mask:0xf
	v_fmac_f32_dpp v16, v129, v95 row_newbcast:15 row_mask:0xf bank_mask:0xf
	v_fmac_f32_dpp v17, v133, v95 row_newbcast:15 row_mask:0xf bank_mask:0xf
	s_waitcnt vmcnt(16)
	v_fmac_f32_dpp v16, v130, v96 row_newbcast:0 row_mask:0xf bank_mask:0xf
	v_fmac_f32_dpp v17, v134, v96 row_newbcast:0 row_mask:0xf bank_mask:0xf
	v_fmac_f32_dpp v16, v130, v97 row_newbcast:1 row_mask:0xf bank_mask:0xf
	v_fmac_f32_dpp v17, v134, v97 row_newbcast:1 row_mask:0xf bank_mask:0xf
	v_fmac_f32_dpp v16, v130, v98 row_newbcast:2 row_mask:0xf bank_mask:0xf
	v_fmac_f32_dpp v17, v134, v98 row_newbcast:2 row_mask:0xf bank_mask:0xf
	v_fmac_f32_dpp v16, v130, v99 row_newbcast:3 row_mask:0xf bank_mask:0xf
	v_fmac_f32_dpp v17, v134, v99 row_newbcast:3 row_mask:0xf bank_mask:0xf
	v_fmac_f32_dpp v16, v130, v100 row_newbcast:4 row_mask:0xf bank_mask:0xf
	v_fmac_f32_dpp v17, v134, v100 row_newbcast:4 row_mask:0xf bank_mask:0xf
	v_fmac_f32_dpp v16, v130, v101 row_newbcast:5 row_mask:0xf bank_mask:0xf
	v_fmac_f32_dpp v17, v134, v101 row_newbcast:5 row_mask:0xf bank_mask:0xf
	v_fmac_f32_dpp v16, v130, v102 row_newbcast:6 row_mask:0xf bank_mask:0xf
	v_fmac_f32_dpp v17, v134, v102 row_newbcast:6 row_mask:0xf bank_mask:0xf
	v_fmac_f32_dpp v16, v130, v103 row_newbcast:7 row_mask:0xf bank_mask:0xf
	v_fmac_f32_dpp v17, v134, v103 row_newbcast:7 row_mask:0xf bank_mask:0xf
	v_fmac_f32_dpp v16, v130, v104 row_newbcast:8 row_mask:0xf bank_mask:0xf
	v_fmac_f32_dpp v17, v134, v104 row_newbcast:8 row_mask:0xf bank_mask:0xf
	v_fmac_f32_dpp v16, v130, v105 row_newbcast:9 row_mask:0xf bank_mask:0xf
	v_fmac_f32_dpp v17, v134, v105 row_newbcast:9 row_mask:0xf bank_mask:0xf
	v_fmac_f32_dpp v16, v130, v106 row_newbcast:10 row_mask:0xf bank_mask:0xf
	v_fmac_f32_dpp v17, v134, v106 row_newbcast:10 row_mask:0xf bank_mask:0xf
	v_fmac_f32_dpp v16, v130, v107 row_newbcast:11 row_mask:0xf bank_mask:0xf
	v_fmac_f32_dpp v17, v134, v107 row_newbcast:11 row_mask:0xf bank_mask:0xf
	v_fmac_f32_dpp v16, v130, v108 row_newbcast:12 row_mask:0xf bank_mask:0xf
	v_fmac_f32_dpp v17, v134, v108 row_newbcast:12 row_mask:0xf bank_mask:0xf
	v_fmac_f32_dpp v16, v130, v109 row_newbcast:13 row_mask:0xf bank_mask:0xf
	v_fmac_f32_dpp v17, v134, v109 row_newbcast:13 row_mask:0xf bank_mask:0xf
	v_fmac_f32_dpp v16, v130, v110 row_newbcast:14 row_mask:0xf bank_mask:0xf
	v_fmac_f32_dpp v17, v134, v110 row_newbcast:14 row_mask:0xf bank_mask:0xf
	v_fmac_f32_dpp v16, v130, v111 row_newbcast:15 row_mask:0xf bank_mask:0xf
	v_fmac_f32_dpp v17, v134, v111 row_newbcast:15 row_mask:0xf bank_mask:0xf
	s_waitcnt vmcnt(0)
	v_fmac_f32_dpp v16, v131, v112 row_newbcast:0 row_mask:0xf bank_mask:0xf
	v_fmac_f32_dpp v17, v135, v112 row_newbcast:0 row_mask:0xf bank_mask:0xf
	v_fmac_f32_dpp v16, v131, v113 row_newbcast:1 row_mask:0xf bank_mask:0xf
	v_fmac_f32_dpp v17, v135, v113 row_newbcast:1 row_mask:0xf bank_mask:0xf
	v_fmac_f32_dpp v16, v131, v114 row_newbcast:2 row_mask:0xf bank_mask:0xf
	v_fmac_f32_dpp v17, v135, v114 row_newbcast:2 row_mask:0xf bank_mask:0xf
	v_fmac_f32_dpp v16, v131, v115 row_newbcast:3 row_mask:0xf bank_mask:0xf
	v_fmac_f32_dpp v17, v135, v115 row_newbcast:3 row_mask:0xf bank_mask:0xf
	v_fmac_f32_dpp v16, v131, v116 row_newbcast:4 row_mask:0xf bank_mask:0xf
	v_fmac_f32_dpp v17, v135, v116 row_newbcast:4 row_mask:0xf bank_mask:0xf
	v_fmac_f32_dpp v16, v131, v117 row_newbcast:5 row_mask:0xf bank_mask:0xf
	v_fmac_f32_dpp v17, v135, v117 row_newbcast:5 row_mask:0xf bank_mask:0xf
	v_fmac_f32_dpp v16, v131, v118 row_newbcast:6 row_mask:0xf bank_mask:0xf
	v_fmac_f32_dpp v17, v135, v118 row_newbcast:6 row_mask:0xf bank_mask:0xf
	v_fmac_f32_dpp v16, v131, v119 row_newbcast:7 row_mask:0xf bank_mask:0xf
	v_fmac_f32_dpp v17, v135, v119 row_newbcast:7 row_mask:0xf bank_mask:0xf
	v_fmac_f32_dpp v16, v131, v120 row_newbcast:8 row_mask:0xf bank_mask:0xf
	v_fmac_f32_dpp v17, v135, v120 row_newbcast:8 row_mask:0xf bank_mask:0xf
	v_fmac_f32_dpp v16, v131, v121 row_newbcast:9 row_mask:0xf bank_mask:0xf
	v_fmac_f32_dpp v17, v135, v121 row_newbcast:9 row_mask:0xf bank_mask:0xf
	v_fmac_f32_dpp v16, v131, v122 row_newbcast:10 row_mask:0xf bank_mask:0xf
	v_fmac_f32_dpp v17, v135, v122 row_newbcast:10 row_mask:0xf bank_mask:0xf
	v_fmac_f32_dpp v16, v131, v123 row_newbcast:11 row_mask:0xf bank_mask:0xf
	v_fmac_f32_dpp v17, v135, v123 row_newbcast:11 row_mask:0xf bank_mask:0xf
	v_fmac_f32_dpp v16, v131, v124 row_newbcast:12 row_mask:0xf bank_mask:0xf
	v_fmac_f32_dpp v17, v135, v124 row_newbcast:12 row_mask:0xf bank_mask:0xf
	v_fmac_f32_dpp v16, v131, v125 row_newbcast:13 row_mask:0xf bank_mask:0xf
	v_fmac_f32_dpp v17, v135, v125 row_newbcast:13 row_mask:0xf bank_mask:0xf
	v_fmac_f32_dpp v16, v131, v126 row_newbcast:14 row_mask:0xf bank_mask:0xf
	v_fmac_f32_dpp v17, v135, v126 row_newbcast:14 row_mask:0xf bank_mask:0xf
	v_fmac_f32_dpp v16, v131, v127 row_newbcast:15 row_mask:0xf bank_mask:0xf
	v_fmac_f32_dpp v17, v135, v127 row_newbcast:15 row_mask:0xf bank_mask:0xf
	v_add_u32_e32 v14, 0, v20
	ds_write_b64 v14, v[16:17] offset:16384
	s_waitcnt lgkmcnt(0)
	s_barrier
	s_and_saveexec_b64 s[24:25], s[8:9]
	s_cbranch_execz .LBB0_2
	s_mul_i32 s40, s12, 0x9000
	v_or_b32_e32 v14, s20, v6
	s_mul_hi_i32 s21, s12, 0x9000
	s_add_u32 s22, s22, s40
	v_ashrrev_i32_e32 v15, 31, v14
	s_addc_u32 s23, s23, s21
	v_lshlrev_b64 v[14:15], 2, v[14:15]
	v_lshl_add_u64 v[16:17], s[22:23], 0, v[14:15]
	global_load_dword v25, v[16:17], off
	ds_read2st64_b32 v[16:17], v21 offset0:64 offset1:66
	ds_read2st64_b32 v[18:19], v21 offset0:68 offset1:70
	ds_read2st64_b32 v[26:27], v21 offset0:72 offset1:74
	ds_read2st64_b32 v[28:29], v21 offset0:76 offset1:78
	v_lshl_or_b32 v32, s12, 1, v23
	s_waitcnt lgkmcnt(3)
	v_add_f32_e32 v16, 0, v16
	v_add_f32_e32 v16, v16, v17
	s_waitcnt lgkmcnt(2)
	v_add_f32_e32 v16, v16, v18
	v_add_f32_e32 v16, v16, v19
	s_waitcnt lgkmcnt(1)
	v_add_f32_e32 v16, v16, v26
	v_add_f32_e32 v16, v16, v27
	v_mov_b64_e32 v[30:31], s[18:19]
	s_waitcnt lgkmcnt(0)
	v_add_f32_e32 v16, v16, v28
	v_mad_i64_i32 v[30:31], s[18:19], v32, s26, v[30:31]
	v_add_f32_e32 v16, v16, v29
	v_lshl_add_u64 v[14:15], v[30:31], 0, v[14:15]
	s_waitcnt vmcnt(0)
	v_add_f32_e32 v16, v16, v25
	global_store_dword v[14:15], v16, off
	s_branch .LBB0_2
